# bundle24 + the 16 ds_reads of each unit's first load segment are issued at the top of the unit-loop header so their LDS latency overlaps the next-tile pointer arithmetic
# baseline (speedup 1.0000x reference)
.LBB0_290:
	ds_read_b128 v[146:149], v153
	ds_read_b128 v[156:159], v153 offset:1024
	ds_read_b128 v[160:163], v153 offset:2048
	ds_read_b128 v[164:167], v153 offset:3072
	ds_read_b128 v[168:171], v154
	ds_read_b128 v[172:175], v154 offset:1024
	ds_read_b128 v[180:183], v154 offset:2048
	ds_read_b128 v[184:187], v154 offset:3072
	ds_read_b128 v[188:191], v155
	ds_read_b128 v[192:195], v155 offset:1024
	ds_read_b128 v[196:199], v155 offset:2048
	ds_read_b128 v[200:203], v155 offset:3072
	ds_read_b128 v[204:207], v155 offset:4096
	ds_read_b128 v[208:211], v155 offset:5120
	ds_read_b128 v[212:215], v155 offset:6144
	ds_read_b128 v[216:219], v155 offset:7168
	s_add_i32 s66, s66, 1
	s_mul_i32 s2, s66, s67
	s_mul_hi_u32 s3, s66, s33
	s_add_i32 s3, s3, s2
	s_mul_i32 s2, s66, s33
	s_add_u32 s14, s2, s18
	s_addc_u32 s15, s3, s31
	v_cmp_gt_i64_e32 vcc, s[14:15], v[144:145]
	v_cmp_lt_i64_e64 s[2:3], s[14:15], v[142:143]
	s_cbranch_vccnz .LBB0_292
	s_ashr_i32 s10, s14, 31
	s_lshr_b32 s10, s10, 29
	s_add_i32 s10, s14, s10
	s_ashr_i32 s11, s10, 3
	s_and_b32 s10, s10, -8
	s_sub_i32 s10, s14, s10
	s_cmp_lt_i32 s10, 0
	s_cselect_b32 s12, s56, 0x2c0
	s_mul_i32 s10, s10, s12
	s_add_i32 s10, s10, s11
	s_mul_hi_i32 s11, s10, 0x2e8ba2e9
	s_lshr_b32 s12, s11, 31
	s_ashr_i32 s11, s11, 6
	s_add_i32 s11, s11, s12
	s_lshl_b32 s12, s11, 3
	s_mulk_i32 s11, 0x160
	s_sub_i32 s11, s10, s11
	s_lshr_b32 s10, s11, 3
	s_and_b32 s11, s11, 7
	s_add_i32 s12, s12, s11
.LBB0_292:
	s_ashr_i32 s13, s12, 31
	s_lshl_b64 s[14:15], s[12:13], 20
	s_add_u32 s14, s19, s14
	s_addc_u32 s15, s22, s15
	s_and_b64 s[16:17], s[2:3], exec
	s_cselect_b32 s13, s15, s41
	s_cselect_b32 s74, s14, s40
	s_ashr_i32 s11, s10, 31
	s_lshl_b64 s[16:17], s[10:11], 20
	s_add_u32 s16, s23, s16
	s_addc_u32 s17, s28, s17
	s_and_b64 s[54:55], s[2:3], exec
	s_cselect_b32 s11, s17, s43
	s_cselect_b32 s75, s16, s42
	s_add_u32 s40, s40, 0x80080
	s_addc_u32 s41, s41, 0
	s_add_u32 s76, s42, 0x100
	s_addc_u32 s77, s43, 0
	s_mov_b32 s78, -2
	s_add_u32 s42, s40, 0xfff80080
	s_addc_u32 s43, s41, -1
	s_cmp_eq_u32 s78, 28
	s_cselect_b32 s55, s13, s43
	s_cselect_b32 s54, s74, s42
	s_cselect_b32 s43, s11, s77
	s_cselect_b32 s42, s75, s76
	s_add_i32 m0, s35, 0xc000
	s_nop 0
	global_load_lds_dwordx4 v138, s[40:41]
	s_add_i32 m0, s35, 0xe000
	s_nop 0
	global_load_lds_dwordx4 v140, s[40:41]
	s_waitcnt vmcnt(8)
	s_waitcnt lgkmcnt(0)
	s_setprio 1
	s_barrier
	v_mfma_f32_16x16x32_bf16 v[126:129], v[146:149], v[188:191], 0
	v_mfma_f32_16x16x32_bf16 v[118:121], v[160:163], v[188:191], 0
	v_mfma_f32_16x16x32_bf16 v[110:113], v[146:149], v[196:199], 0
	v_mfma_f32_16x16x32_bf16 v[102:105], v[160:163], v[196:199], 0
	v_mfma_f32_16x16x32_bf16 v[94:97], v[146:149], v[204:207], 0
	v_mfma_f32_16x16x32_bf16 v[86:89], v[160:163], v[204:207], 0
	v_mfma_f32_16x16x32_bf16 v[78:81], v[146:149], v[212:215], 0
	v_mfma_f32_16x16x32_bf16 v[70:73], v[160:163], v[212:215], 0
	v_mfma_f32_16x16x32_bf16 v[126:129], v[156:159], v[192:195], v[126:129]
	v_mfma_f32_16x16x32_bf16 v[118:121], v[164:167], v[192:195], v[118:121]
	v_mfma_f32_16x16x32_bf16 v[110:113], v[156:159], v[200:203], v[110:113]
	v_mfma_f32_16x16x32_bf16 v[102:105], v[164:167], v[200:203], v[102:105]
	v_mfma_f32_16x16x32_bf16 v[94:97], v[156:159], v[208:211], v[94:97]
	v_mfma_f32_16x16x32_bf16 v[86:89], v[164:167], v[208:211], v[86:89]
	v_mfma_f32_16x16x32_bf16 v[78:81], v[156:159], v[216:219], v[78:81]
	v_mfma_f32_16x16x32_bf16 v[70:73], v[164:167], v[216:219], v[70:73]
	s_setprio 0
	s_setprio 1
	v_mfma_f32_16x16x32_bf16 v[122:125], v[168:171], v[188:191], 0
	v_mfma_f32_16x16x32_bf16 v[114:117], v[180:183], v[188:191], 0
	v_mfma_f32_16x16x32_bf16 v[106:109], v[168:171], v[196:199], 0
	v_mfma_f32_16x16x32_bf16 v[98:101], v[180:183], v[196:199], 0
	v_mfma_f32_16x16x32_bf16 v[90:93], v[168:171], v[204:207], 0
	v_mfma_f32_16x16x32_bf16 v[82:85], v[180:183], v[204:207], 0
	v_mfma_f32_16x16x32_bf16 v[74:77], v[168:171], v[212:215], 0
	v_mfma_f32_16x16x32_bf16 v[66:69], v[180:183], v[212:215], 0
	v_mfma_f32_16x16x32_bf16 v[122:125], v[172:175], v[192:195], v[122:125]
	v_mfma_f32_16x16x32_bf16 v[114:117], v[184:187], v[192:195], v[114:117]
	v_mfma_f32_16x16x32_bf16 v[106:109], v[172:175], v[200:203], v[106:109]
	v_mfma_f32_16x16x32_bf16 v[98:101], v[184:187], v[200:203], v[98:101]
	v_mfma_f32_16x16x32_bf16 v[90:93], v[172:175], v[208:211], v[90:93]
	v_mfma_f32_16x16x32_bf16 v[82:85], v[184:187], v[208:211], v[82:85]
	v_mfma_f32_16x16x32_bf16 v[74:77], v[172:175], v[216:219], v[74:77]
	v_mfma_f32_16x16x32_bf16 v[66:69], v[184:187], v[216:219], v[66:69]
	s_barrier
	s_setprio 0
	s_add_i32 s79, s70, s29
	s_add_u32 s98, s42, 0x80
	s_addc_u32 s99, s43, 0
	s_mov_b32 m0, s79
	ds_read_b128 v[188:191], v155 offset:16384
	ds_read_b128 v[192:195], v155 offset:17408
	ds_read_b128 v[196:199], v155 offset:18432
	ds_read_b128 v[200:203], v155 offset:19456
	ds_read_b128 v[204:207], v155 offset:20480
	ds_read_b128 v[208:211], v155 offset:21504
	ds_read_b128 v[212:215], v155 offset:22528
	ds_read_b128 v[216:219], v155 offset:23552
	global_load_lds_dwordx4 v134, s[42:43]
	s_add_i32 m0, s79, 0x2000
	s_add_u32 s80, s42, 0x80000
	s_addc_u32 s81, s43, 0
	s_add_i32 s79, s71, s29
	global_load_lds_dwordx4 v130, s[42:43]
	s_mov_b32 m0, s79
	s_nop 0
	global_load_lds_dwordx4 v134, s[80:81]
	s_add_i32 m0, s79, 0x2000
	s_nop 0
	global_load_lds_dwordx4 v130, s[80:81]
	s_add_u32 s100, s54, 0x80
	s_addc_u32 s101, s55, 0
	s_mov_b32 m0, s35
	s_nop 0
	global_load_lds_dwordx4 v136, s[54:55]
	s_mov_b32 m0, s57
	s_nop 0
	global_load_lds_dwordx4 v132, s[54:55]
	s_waitcnt vmcnt(8)
	s_waitcnt lgkmcnt(0)
	s_setprio 1
	s_barrier
	v_mfma_f32_16x16x32_bf16 v[62:65], v[146:149], v[188:191], 0
	v_mfma_f32_16x16x32_bf16 v[54:57], v[160:163], v[188:191], 0
	v_mfma_f32_16x16x32_bf16 v[46:49], v[146:149], v[196:199], 0
	v_mfma_f32_16x16x32_bf16 v[38:41], v[160:163], v[196:199], 0
	v_mfma_f32_16x16x32_bf16 v[30:33], v[146:149], v[204:207], 0
	v_mfma_f32_16x16x32_bf16 v[22:25], v[160:163], v[204:207], 0
	v_mfma_f32_16x16x32_bf16 v[14:17], v[146:149], v[212:215], 0
	v_mfma_f32_16x16x32_bf16 v[6:9], v[160:163], v[212:215], 0
	v_mfma_f32_16x16x32_bf16 v[62:65], v[156:159], v[192:195], v[62:65]
	v_mfma_f32_16x16x32_bf16 v[54:57], v[164:167], v[192:195], v[54:57]
	v_mfma_f32_16x16x32_bf16 v[46:49], v[156:159], v[200:203], v[46:49]
	v_mfma_f32_16x16x32_bf16 v[38:41], v[164:167], v[200:203], v[38:41]
	v_mfma_f32_16x16x32_bf16 v[30:33], v[156:159], v[208:211], v[30:33]
	v_mfma_f32_16x16x32_bf16 v[22:25], v[164:167], v[208:211], v[22:25]
	v_mfma_f32_16x16x32_bf16 v[14:17], v[156:159], v[216:219], v[14:17]
	v_mfma_f32_16x16x32_bf16 v[6:9], v[164:167], v[216:219], v[6:9]
	s_setprio 0
	s_setprio 1
	v_mfma_f32_16x16x32_bf16 v[58:61], v[168:171], v[188:191], 0
	v_mfma_f32_16x16x32_bf16 v[50:53], v[180:183], v[188:191], 0
	v_mfma_f32_16x16x32_bf16 v[42:45], v[168:171], v[196:199], 0
	v_mfma_f32_16x16x32_bf16 v[34:37], v[180:183], v[196:199], 0
	v_mfma_f32_16x16x32_bf16 v[26:29], v[168:171], v[204:207], 0
	v_mfma_f32_16x16x32_bf16 v[18:21], v[180:183], v[204:207], 0
	v_mfma_f32_16x16x32_bf16 v[10:13], v[168:171], v[212:215], 0
	v_mfma_f32_16x16x32_bf16 v[2:5], v[180:183], v[212:215], 0
	v_mfma_f32_16x16x32_bf16 v[58:61], v[172:175], v[192:195], v[58:61]
	v_mfma_f32_16x16x32_bf16 v[50:53], v[184:187], v[192:195], v[50:53]
	v_mfma_f32_16x16x32_bf16 v[42:45], v[172:175], v[200:203], v[42:45]
	v_mfma_f32_16x16x32_bf16 v[34:37], v[184:187], v[200:203], v[34:37]
	v_mfma_f32_16x16x32_bf16 v[26:29], v[172:175], v[208:211], v[26:29]
	v_mfma_f32_16x16x32_bf16 v[18:21], v[184:187], v[208:211], v[18:21]
	v_mfma_f32_16x16x32_bf16 v[10:13], v[172:175], v[216:219], v[10:13]
	v_mfma_f32_16x16x32_bf16 v[2:5], v[184:187], v[216:219], v[2:5]
	s_barrier
	s_setprio 0
	s_add_i32 s79, 0, 0x18000
	s_add_i32 s80, 0, 0x1c000
	ds_read_b128 v[146:149], v153 offset:32768
	ds_read_b128 v[156:159], v153 offset:33792
	ds_read_b128 v[160:163], v153 offset:34816
	ds_read_b128 v[164:167], v153 offset:35840
	ds_read_b128 v[168:171], v154 offset:32768
	ds_read_b128 v[172:175], v154 offset:33792
	ds_read_b128 v[180:183], v154 offset:34816
	ds_read_b128 v[184:187], v154 offset:35840
	s_add_u32 s54, s54, 0x80000
	s_addc_u32 s55, s55, 0
	s_mov_b32 m0, s58
	ds_read_b128 v[188:191], v155 offset:32768
	ds_read_b128 v[192:195], v155 offset:33792
	ds_read_b128 v[196:199], v155 offset:34816
	ds_read_b128 v[200:203], v155 offset:35840
	ds_read_b128 v[204:207], v155 offset:36864
	ds_read_b128 v[208:211], v155 offset:37888
	ds_read_b128 v[212:215], v155 offset:38912
	ds_read_b128 v[216:219], v155 offset:39936
	global_load_lds_dwordx4 v136, s[54:55]
	s_mov_b32 m0, s59
	s_nop 0
	global_load_lds_dwordx4 v132, s[54:55]
	s_waitcnt vmcnt(8)
	s_waitcnt lgkmcnt(0)
	s_setprio 1
	s_barrier
	v_mfma_f32_16x16x32_bf16 v[126:129], v[146:149], v[188:191], v[126:129]
	v_mfma_f32_16x16x32_bf16 v[118:121], v[160:163], v[188:191], v[118:121]
	v_mfma_f32_16x16x32_bf16 v[110:113], v[146:149], v[196:199], v[110:113]
	v_mfma_f32_16x16x32_bf16 v[102:105], v[160:163], v[196:199], v[102:105]
	v_mfma_f32_16x16x32_bf16 v[94:97], v[146:149], v[204:207], v[94:97]
	v_mfma_f32_16x16x32_bf16 v[86:89], v[160:163], v[204:207], v[86:89]
	v_mfma_f32_16x16x32_bf16 v[78:81], v[146:149], v[212:215], v[78:81]
	v_mfma_f32_16x16x32_bf16 v[70:73], v[160:163], v[212:215], v[70:73]
	v_mfma_f32_16x16x32_bf16 v[126:129], v[156:159], v[192:195], v[126:129]
	v_mfma_f32_16x16x32_bf16 v[118:121], v[164:167], v[192:195], v[118:121]
	v_mfma_f32_16x16x32_bf16 v[110:113], v[156:159], v[200:203], v[110:113]
	v_mfma_f32_16x16x32_bf16 v[102:105], v[164:167], v[200:203], v[102:105]
	v_mfma_f32_16x16x32_bf16 v[94:97], v[156:159], v[208:211], v[94:97]
	v_mfma_f32_16x16x32_bf16 v[86:89], v[164:167], v[208:211], v[86:89]
	v_mfma_f32_16x16x32_bf16 v[78:81], v[156:159], v[216:219], v[78:81]
	v_mfma_f32_16x16x32_bf16 v[70:73], v[164:167], v[216:219], v[70:73]
	s_setprio 0
	s_setprio 1
	v_mfma_f32_16x16x32_bf16 v[122:125], v[168:171], v[188:191], v[122:125]
	v_mfma_f32_16x16x32_bf16 v[114:117], v[180:183], v[188:191], v[114:117]
	v_mfma_f32_16x16x32_bf16 v[106:109], v[168:171], v[196:199], v[106:109]
	v_mfma_f32_16x16x32_bf16 v[98:101], v[180:183], v[196:199], v[98:101]
	v_mfma_f32_16x16x32_bf16 v[90:93], v[168:171], v[204:207], v[90:93]
	v_mfma_f32_16x16x32_bf16 v[82:85], v[180:183], v[204:207], v[82:85]
	v_mfma_f32_16x16x32_bf16 v[74:77], v[168:171], v[212:215], v[74:77]
	v_mfma_f32_16x16x32_bf16 v[66:69], v[180:183], v[212:215], v[66:69]
	v_mfma_f32_16x16x32_bf16 v[122:125], v[172:175], v[192:195], v[122:125]
	v_mfma_f32_16x16x32_bf16 v[114:117], v[184:187], v[192:195], v[114:117]
	v_mfma_f32_16x16x32_bf16 v[106:109], v[172:175], v[200:203], v[106:109]
	v_mfma_f32_16x16x32_bf16 v[98:101], v[184:187], v[200:203], v[98:101]
	v_mfma_f32_16x16x32_bf16 v[90:93], v[172:175], v[208:211], v[90:93]
	v_mfma_f32_16x16x32_bf16 v[82:85], v[184:187], v[208:211], v[82:85]
	v_mfma_f32_16x16x32_bf16 v[74:77], v[172:175], v[216:219], v[74:77]
	v_mfma_f32_16x16x32_bf16 v[66:69], v[184:187], v[216:219], v[66:69]
	s_barrier
	s_setprio 0
	s_add_i32 s54, s79, s29
	s_mov_b32 m0, s54
	ds_read_b128 v[188:191], v155 offset:49152
	ds_read_b128 v[192:195], v155 offset:50176
	ds_read_b128 v[196:199], v155 offset:51200
	ds_read_b128 v[200:203], v155 offset:52224
	ds_read_b128 v[204:207], v155 offset:53248
	ds_read_b128 v[208:211], v155 offset:54272
	ds_read_b128 v[212:215], v155 offset:55296
	ds_read_b128 v[216:219], v155 offset:56320
	global_load_lds_dwordx4 v134, s[98:99]
	s_add_i32 m0, s54, 0x2000
	s_add_u32 s42, s42, 0x80080
	s_addc_u32 s43, s43, 0
	s_add_i32 s54, s80, s29
	global_load_lds_dwordx4 v130, s[98:99]
	s_mov_b32 m0, s54
	s_nop 0
	global_load_lds_dwordx4 v134, s[42:43]
	s_add_i32 m0, s54, 0x2000
	s_nop 0
	global_load_lds_dwordx4 v130, s[42:43]
	s_mov_b32 m0, s64
	s_nop 0
	global_load_lds_dwordx4 v136, s[100:101]
	s_mov_b32 m0, s65
	s_nop 0
	global_load_lds_dwordx4 v132, s[100:101]
	s_waitcnt vmcnt(8)
	s_waitcnt lgkmcnt(0)
	s_setprio 1
	s_barrier
	v_mfma_f32_16x16x32_bf16 v[62:65], v[146:149], v[188:191], v[62:65]
	v_mfma_f32_16x16x32_bf16 v[54:57], v[160:163], v[188:191], v[54:57]
	v_mfma_f32_16x16x32_bf16 v[46:49], v[146:149], v[196:199], v[46:49]
	v_mfma_f32_16x16x32_bf16 v[38:41], v[160:163], v[196:199], v[38:41]
	v_mfma_f32_16x16x32_bf16 v[30:33], v[146:149], v[204:207], v[30:33]
	v_mfma_f32_16x16x32_bf16 v[22:25], v[160:163], v[204:207], v[22:25]
	v_mfma_f32_16x16x32_bf16 v[14:17], v[146:149], v[212:215], v[14:17]
	v_mfma_f32_16x16x32_bf16 v[6:9], v[160:163], v[212:215], v[6:9]
	v_mfma_f32_16x16x32_bf16 v[62:65], v[156:159], v[192:195], v[62:65]
	v_mfma_f32_16x16x32_bf16 v[54:57], v[164:167], v[192:195], v[54:57]
	v_mfma_f32_16x16x32_bf16 v[46:49], v[156:159], v[200:203], v[46:49]
	v_mfma_f32_16x16x32_bf16 v[38:41], v[164:167], v[200:203], v[38:41]
	v_mfma_f32_16x16x32_bf16 v[30:33], v[156:159], v[208:211], v[30:33]
	v_mfma_f32_16x16x32_bf16 v[22:25], v[164:167], v[208:211], v[22:25]
	v_mfma_f32_16x16x32_bf16 v[14:17], v[156:159], v[216:219], v[14:17]
	v_mfma_f32_16x16x32_bf16 v[6:9], v[164:167], v[216:219], v[6:9]
	s_setprio 0
	s_setprio 1
	v_mfma_f32_16x16x32_bf16 v[58:61], v[168:171], v[188:191], v[58:61]
	v_mfma_f32_16x16x32_bf16 v[50:53], v[180:183], v[188:191], v[50:53]
	v_mfma_f32_16x16x32_bf16 v[42:45], v[168:171], v[196:199], v[42:45]
	v_mfma_f32_16x16x32_bf16 v[34:37], v[180:183], v[196:199], v[34:37]
	v_mfma_f32_16x16x32_bf16 v[26:29], v[168:171], v[204:207], v[26:29]
	v_mfma_f32_16x16x32_bf16 v[18:21], v[180:183], v[204:207], v[18:21]
	v_mfma_f32_16x16x32_bf16 v[10:13], v[168:171], v[212:215], v[10:13]
	v_mfma_f32_16x16x32_bf16 v[2:5], v[180:183], v[212:215], v[2:5]
	v_mfma_f32_16x16x32_bf16 v[58:61], v[172:175], v[192:195], v[58:61]
	v_mfma_f32_16x16x32_bf16 v[50:53], v[184:187], v[192:195], v[50:53]
	v_mfma_f32_16x16x32_bf16 v[42:45], v[172:175], v[200:203], v[42:45]
	v_mfma_f32_16x16x32_bf16 v[34:37], v[184:187], v[200:203], v[34:37]
	v_mfma_f32_16x16x32_bf16 v[26:29], v[172:175], v[208:211], v[26:29]
	v_mfma_f32_16x16x32_bf16 v[18:21], v[184:187], v[208:211], v[18:21]
	v_mfma_f32_16x16x32_bf16 v[10:13], v[172:175], v[216:219], v[10:13]
	v_mfma_f32_16x16x32_bf16 v[2:5], v[184:187], v[216:219], v[2:5]
	s_barrier
	s_setprio 0
	s_add_i32 s78, s78, 2
	s_add_u32 s40, s40, 0x100
	s_addc_u32 s41, s41, 0
	s_add_u32 s76, s76, 0x100
	s_addc_u32 s77, s77, 0
	s_cmp_gt_u32 s78, 29

.LBB0_368:
	ds_read_b128 v[130:133], v208
	ds_read_b128 v[134:137], v208 offset:1024
	ds_read_b128 v[138:141], v208 offset:2048
	ds_read_b128 v[142:145], v208 offset:3072
	ds_read_b128 v[146:149], v209
	ds_read_b128 v[150:153], v209 offset:1024
	ds_read_b128 v[154:157], v209 offset:2048
	ds_read_b128 v[158:161], v209 offset:3072
	ds_read_b128 v[162:165], v210
	ds_read_b128 v[166:169], v210 offset:1024
	ds_read_b128 v[170:173], v210 offset:2048
	ds_read_b128 v[174:177], v210 offset:3072
	ds_read_b128 v[196:199], v210 offset:4096
	ds_read_b128 v[200:203], v210 offset:5120
	ds_read_b128 v[212:215], v210 offset:6144
	ds_read_b128 v[216:219], v210 offset:7168
	s_add_i32 s67, s67, 1
	s_mul_i32 s10, s67, s73
	s_mul_hi_u32 s11, s67, s33
	s_add_i32 s11, s11, s10
	s_mul_i32 s10, s67, s33
	s_add_u32 s10, s10, s18
	s_addc_u32 s11, s11, s74
	v_cmp_gt_i64_e32 vcc, s[10:11], v[194:195]
	v_cmp_lt_i64_e64 s[12:13], s[10:11], v[192:193]
	s_cbranch_vccnz .LBB0_374
	s_ashr_i32 s11, s10, 31
	s_lshr_b32 s11, s11, 29
	s_add_i32 s42, s10, s11
	s_and_b32 s11, s42, -8
	s_sub_i32 s43, s10, s11
	s_cmp_gt_i32 s43, -1
	s_mov_b64 s[10:11], -1
	s_cbranch_scc0 .LBB0_371
	s_lshl_b32 s54, s43, 7
	s_mov_b64 s[10:11], 0

.LBB0_378:
	s_add_u32 s12, s58, 0x160080
	s_addc_u32 s13, s59, 0
	s_add_u32 s81, s56, 0x100
	s_addc_u32 s82, s57, 0
	s_mov_b32 s83, -2
	s_add_u32 s56, s12, 0xffea0080
	s_addc_u32 s57, s13, -1
	s_cmpk_eq_i32 s83, 0x54
	s_cselect_b32 s59, s43, s57
	s_cselect_b32 s58, s42, s56
	s_cselect_b32 s57, s55, s82
	s_cselect_b32 s56, s54, s81
	s_add_i32 m0, s31, 0xc000
	s_nop 0
	global_load_lds_dwordx4 v188, s[12:13]
	s_add_i32 m0, s31, 0xe000
	s_nop 0
	global_load_lds_dwordx4 v190, s[12:13]
	s_waitcnt vmcnt(8)
	s_waitcnt lgkmcnt(0)
	s_setprio 1
	s_barrier
	v_mfma_f32_16x16x32_bf16 v[126:129], v[130:133], v[162:165], 0
	v_mfma_f32_16x16x32_bf16 v[122:125], v[138:141], v[162:165], 0
	v_mfma_f32_16x16x32_bf16 v[110:113], v[130:133], v[170:173], 0
	v_mfma_f32_16x16x32_bf16 v[106:109], v[138:141], v[170:173], 0
	v_mfma_f32_16x16x32_bf16 v[94:97], v[130:133], v[196:199], 0
	v_mfma_f32_16x16x32_bf16 v[90:93], v[138:141], v[196:199], 0
	v_mfma_f32_16x16x32_bf16 v[78:81], v[130:133], v[212:215], 0
	v_mfma_f32_16x16x32_bf16 v[74:77], v[138:141], v[212:215], 0
	v_mfma_f32_16x16x32_bf16 v[126:129], v[134:137], v[166:169], v[126:129]
	v_mfma_f32_16x16x32_bf16 v[122:125], v[142:145], v[166:169], v[122:125]
	v_mfma_f32_16x16x32_bf16 v[110:113], v[134:137], v[174:177], v[110:113]
	v_mfma_f32_16x16x32_bf16 v[106:109], v[142:145], v[174:177], v[106:109]
	v_mfma_f32_16x16x32_bf16 v[94:97], v[134:137], v[200:203], v[94:97]
	v_mfma_f32_16x16x32_bf16 v[90:93], v[142:145], v[200:203], v[90:93]
	v_mfma_f32_16x16x32_bf16 v[78:81], v[134:137], v[216:219], v[78:81]
	v_mfma_f32_16x16x32_bf16 v[74:77], v[142:145], v[216:219], v[74:77]
	s_setprio 0
	s_setprio 1
	v_mfma_f32_16x16x32_bf16 v[118:121], v[146:149], v[162:165], 0
	v_mfma_f32_16x16x32_bf16 v[114:117], v[154:157], v[162:165], 0
	v_mfma_f32_16x16x32_bf16 v[102:105], v[146:149], v[170:173], 0
	v_mfma_f32_16x16x32_bf16 v[98:101], v[154:157], v[170:173], 0
	v_mfma_f32_16x16x32_bf16 v[86:89], v[146:149], v[196:199], 0
	v_mfma_f32_16x16x32_bf16 v[82:85], v[154:157], v[196:199], 0
	v_mfma_f32_16x16x32_bf16 v[70:73], v[146:149], v[212:215], 0
	v_mfma_f32_16x16x32_bf16 v[66:69], v[154:157], v[212:215], 0
	v_mfma_f32_16x16x32_bf16 v[118:121], v[150:153], v[166:169], v[118:121]
	v_mfma_f32_16x16x32_bf16 v[114:117], v[158:161], v[166:169], v[114:117]
	v_mfma_f32_16x16x32_bf16 v[102:105], v[150:153], v[174:177], v[102:105]
	v_mfma_f32_16x16x32_bf16 v[98:101], v[158:161], v[174:177], v[98:101]
	v_mfma_f32_16x16x32_bf16 v[86:89], v[150:153], v[200:203], v[86:89]
	v_mfma_f32_16x16x32_bf16 v[82:85], v[158:161], v[200:203], v[82:85]
	v_mfma_f32_16x16x32_bf16 v[70:73], v[150:153], v[216:219], v[70:73]
	v_mfma_f32_16x16x32_bf16 v[66:69], v[158:161], v[216:219], v[66:69]
	s_barrier
	s_setprio 0
	s_add_i32 s85, s75, s29
	s_add_u32 s98, s56, 0x80
	s_addc_u32 s99, s57, 0
	s_mov_b32 m0, s85
	ds_read_b128 v[162:165], v210 offset:16384
	ds_read_b128 v[166:169], v210 offset:17408
	ds_read_b128 v[170:173], v210 offset:18432
	ds_read_b128 v[174:177], v210 offset:19456
	ds_read_b128 v[196:199], v210 offset:20480
	ds_read_b128 v[200:203], v210 offset:21504
	ds_read_b128 v[212:215], v210 offset:22528
	ds_read_b128 v[216:219], v210 offset:23552
	global_load_lds_dwordx4 v182, s[56:57]
	s_add_i32 m0, s85, 0x2000
	s_add_u32 s88, s56, 0x160000
	s_addc_u32 s89, s57, 0
	s_add_i32 s85, s76, s29
	global_load_lds_dwordx4 v186, s[56:57]
	s_mov_b32 m0, s85
	s_nop 0
	global_load_lds_dwordx4 v182, s[88:89]
	s_add_i32 m0, s85, 0x2000
	s_nop 0
	global_load_lds_dwordx4 v186, s[88:89]
	s_add_u32 s100, s58, 0x80
	s_addc_u32 s101, s59, 0
	s_mov_b32 m0, s31
	s_nop 0
	global_load_lds_dwordx4 v180, s[58:59]
	s_mov_b32 m0, s64
	s_nop 0
	global_load_lds_dwordx4 v184, s[58:59]
	s_waitcnt vmcnt(8)
	s_waitcnt lgkmcnt(0)
	s_setprio 1
	s_barrier
	v_mfma_f32_16x16x32_bf16 v[62:65], v[130:133], v[162:165], 0
	v_mfma_f32_16x16x32_bf16 v[58:61], v[138:141], v[162:165], 0
	v_mfma_f32_16x16x32_bf16 v[46:49], v[130:133], v[170:173], 0
	v_mfma_f32_16x16x32_bf16 v[42:45], v[138:141], v[170:173], 0
	v_mfma_f32_16x16x32_bf16 v[30:33], v[130:133], v[196:199], 0
	v_mfma_f32_16x16x32_bf16 v[26:29], v[138:141], v[196:199], 0
	v_mfma_f32_16x16x32_bf16 v[14:17], v[130:133], v[212:215], 0
	v_mfma_f32_16x16x32_bf16 v[10:13], v[138:141], v[212:215], 0
	v_mfma_f32_16x16x32_bf16 v[62:65], v[134:137], v[166:169], v[62:65]
	v_mfma_f32_16x16x32_bf16 v[58:61], v[142:145], v[166:169], v[58:61]
	v_mfma_f32_16x16x32_bf16 v[46:49], v[134:137], v[174:177], v[46:49]
	v_mfma_f32_16x16x32_bf16 v[42:45], v[142:145], v[174:177], v[42:45]
	v_mfma_f32_16x16x32_bf16 v[30:33], v[134:137], v[200:203], v[30:33]
	v_mfma_f32_16x16x32_bf16 v[26:29], v[142:145], v[200:203], v[26:29]
	v_mfma_f32_16x16x32_bf16 v[14:17], v[134:137], v[216:219], v[14:17]
	v_mfma_f32_16x16x32_bf16 v[10:13], v[142:145], v[216:219], v[10:13]
	s_setprio 0
	s_setprio 1
	v_mfma_f32_16x16x32_bf16 v[54:57], v[146:149], v[162:165], 0
	v_mfma_f32_16x16x32_bf16 v[50:53], v[154:157], v[162:165], 0
	v_mfma_f32_16x16x32_bf16 v[38:41], v[146:149], v[170:173], 0
	v_mfma_f32_16x16x32_bf16 v[34:37], v[154:157], v[170:173], 0
	v_mfma_f32_16x16x32_bf16 v[22:25], v[146:149], v[196:199], 0
	v_mfma_f32_16x16x32_bf16 v[18:21], v[154:157], v[196:199], 0
	v_mfma_f32_16x16x32_bf16 v[6:9], v[146:149], v[212:215], 0
	v_mfma_f32_16x16x32_bf16 v[2:5], v[154:157], v[212:215], 0
	v_mfma_f32_16x16x32_bf16 v[54:57], v[150:153], v[166:169], v[54:57]
	v_mfma_f32_16x16x32_bf16 v[50:53], v[158:161], v[166:169], v[50:53]
	v_mfma_f32_16x16x32_bf16 v[38:41], v[150:153], v[174:177], v[38:41]
	v_mfma_f32_16x16x32_bf16 v[34:37], v[158:161], v[174:177], v[34:37]
	v_mfma_f32_16x16x32_bf16 v[22:25], v[150:153], v[200:203], v[22:25]
	v_mfma_f32_16x16x32_bf16 v[18:21], v[158:161], v[200:203], v[18:21]
	v_mfma_f32_16x16x32_bf16 v[6:9], v[150:153], v[216:219], v[6:9]
	v_mfma_f32_16x16x32_bf16 v[2:5], v[158:161], v[216:219], v[2:5]
	s_barrier
	s_setprio 0
	s_add_i32 s85, 0, 0x18000
	s_add_i32 s87, 0, 0x1c000
	ds_read_b128 v[130:133], v208 offset:32768
	ds_read_b128 v[134:137], v208 offset:33792
	ds_read_b128 v[138:141], v208 offset:34816
	ds_read_b128 v[142:145], v208 offset:35840
	ds_read_b128 v[146:149], v209 offset:32768
	ds_read_b128 v[150:153], v209 offset:33792
	ds_read_b128 v[154:157], v209 offset:34816
	ds_read_b128 v[158:161], v209 offset:35840
	s_add_u32 s58, s58, 0x160000
	s_addc_u32 s59, s59, 0
	s_mov_b32 m0, s65
	ds_read_b128 v[162:165], v210 offset:32768
	ds_read_b128 v[166:169], v210 offset:33792
	ds_read_b128 v[170:173], v210 offset:34816
	ds_read_b128 v[174:177], v210 offset:35840
	ds_read_b128 v[196:199], v210 offset:36864
	ds_read_b128 v[200:203], v210 offset:37888
	ds_read_b128 v[212:215], v210 offset:38912
	ds_read_b128 v[216:219], v210 offset:39936
	global_load_lds_dwordx4 v180, s[58:59]
	s_mov_b32 m0, s66
	s_nop 0
	global_load_lds_dwordx4 v184, s[58:59]
	s_waitcnt vmcnt(8)
	s_waitcnt lgkmcnt(0)
	s_setprio 1
	s_barrier
	v_mfma_f32_16x16x32_bf16 v[126:129], v[130:133], v[162:165], v[126:129]
	v_mfma_f32_16x16x32_bf16 v[122:125], v[138:141], v[162:165], v[122:125]
	v_mfma_f32_16x16x32_bf16 v[110:113], v[130:133], v[170:173], v[110:113]
	v_mfma_f32_16x16x32_bf16 v[106:109], v[138:141], v[170:173], v[106:109]
	v_mfma_f32_16x16x32_bf16 v[94:97], v[130:133], v[196:199], v[94:97]
	v_mfma_f32_16x16x32_bf16 v[90:93], v[138:141], v[196:199], v[90:93]
	v_mfma_f32_16x16x32_bf16 v[78:81], v[130:133], v[212:215], v[78:81]
	v_mfma_f32_16x16x32_bf16 v[74:77], v[138:141], v[212:215], v[74:77]
	v_mfma_f32_16x16x32_bf16 v[126:129], v[134:137], v[166:169], v[126:129]
	v_mfma_f32_16x16x32_bf16 v[122:125], v[142:145], v[166:169], v[122:125]
	v_mfma_f32_16x16x32_bf16 v[110:113], v[134:137], v[174:177], v[110:113]
	v_mfma_f32_16x16x32_bf16 v[106:109], v[142:145], v[174:177], v[106:109]
	v_mfma_f32_16x16x32_bf16 v[94:97], v[134:137], v[200:203], v[94:97]
	v_mfma_f32_16x16x32_bf16 v[90:93], v[142:145], v[200:203], v[90:93]
	v_mfma_f32_16x16x32_bf16 v[78:81], v[134:137], v[216:219], v[78:81]
	v_mfma_f32_16x16x32_bf16 v[74:77], v[142:145], v[216:219], v[74:77]
	s_setprio 0
	s_setprio 1
	v_mfma_f32_16x16x32_bf16 v[118:121], v[146:149], v[162:165], v[118:121]
	v_mfma_f32_16x16x32_bf16 v[114:117], v[154:157], v[162:165], v[114:117]
	v_mfma_f32_16x16x32_bf16 v[102:105], v[146:149], v[170:173], v[102:105]
	v_mfma_f32_16x16x32_bf16 v[98:101], v[154:157], v[170:173], v[98:101]
	v_mfma_f32_16x16x32_bf16 v[86:89], v[146:149], v[196:199], v[86:89]
	v_mfma_f32_16x16x32_bf16 v[82:85], v[154:157], v[196:199], v[82:85]
	v_mfma_f32_16x16x32_bf16 v[70:73], v[146:149], v[212:215], v[70:73]
	v_mfma_f32_16x16x32_bf16 v[66:69], v[154:157], v[212:215], v[66:69]
	v_mfma_f32_16x16x32_bf16 v[118:121], v[150:153], v[166:169], v[118:121]
	v_mfma_f32_16x16x32_bf16 v[114:117], v[158:161], v[166:169], v[114:117]
	v_mfma_f32_16x16x32_bf16 v[102:105], v[150:153], v[174:177], v[102:105]
	v_mfma_f32_16x16x32_bf16 v[98:101], v[158:161], v[174:177], v[98:101]
	v_mfma_f32_16x16x32_bf16 v[86:89], v[150:153], v[200:203], v[86:89]
	v_mfma_f32_16x16x32_bf16 v[82:85], v[158:161], v[200:203], v[82:85]
	v_mfma_f32_16x16x32_bf16 v[70:73], v[150:153], v[216:219], v[70:73]
	v_mfma_f32_16x16x32_bf16 v[66:69], v[158:161], v[216:219], v[66:69]
	s_barrier
	s_setprio 0
	s_add_i32 s58, s85, s29
	s_mov_b32 m0, s58
	ds_read_b128 v[162:165], v210 offset:49152
	ds_read_b128 v[166:169], v210 offset:50176
	ds_read_b128 v[170:173], v210 offset:51200
	ds_read_b128 v[174:177], v210 offset:52224
	ds_read_b128 v[196:199], v210 offset:53248
	ds_read_b128 v[200:203], v210 offset:54272
	ds_read_b128 v[212:215], v210 offset:55296
	ds_read_b128 v[216:219], v210 offset:56320
	global_load_lds_dwordx4 v182, s[98:99]
	s_add_i32 m0, s58, 0x2000
	s_add_u32 s56, s56, 0x160080
	s_addc_u32 s57, s57, 0
	s_add_i32 s58, s87, s29
	global_load_lds_dwordx4 v186, s[98:99]
	s_mov_b32 m0, s58
	s_nop 0
	global_load_lds_dwordx4 v182, s[56:57]
	s_add_i32 m0, s58, 0x2000
	s_nop 0
	global_load_lds_dwordx4 v186, s[56:57]
	s_mov_b32 m0, s71
	s_nop 0
	global_load_lds_dwordx4 v180, s[100:101]
	s_mov_b32 m0, s72
	s_nop 0
	global_load_lds_dwordx4 v184, s[100:101]
	s_waitcnt vmcnt(8)
	s_waitcnt lgkmcnt(0)
	s_setprio 1
	s_barrier
	v_mfma_f32_16x16x32_bf16 v[62:65], v[130:133], v[162:165], v[62:65]
	v_mfma_f32_16x16x32_bf16 v[58:61], v[138:141], v[162:165], v[58:61]
	v_mfma_f32_16x16x32_bf16 v[46:49], v[130:133], v[170:173], v[46:49]
	v_mfma_f32_16x16x32_bf16 v[42:45], v[138:141], v[170:173], v[42:45]
	v_mfma_f32_16x16x32_bf16 v[30:33], v[130:133], v[196:199], v[30:33]
	v_mfma_f32_16x16x32_bf16 v[26:29], v[138:141], v[196:199], v[26:29]
	v_mfma_f32_16x16x32_bf16 v[14:17], v[130:133], v[212:215], v[14:17]
	v_mfma_f32_16x16x32_bf16 v[10:13], v[138:141], v[212:215], v[10:13]
	v_mfma_f32_16x16x32_bf16 v[62:65], v[134:137], v[166:169], v[62:65]
	v_mfma_f32_16x16x32_bf16 v[58:61], v[142:145], v[166:169], v[58:61]
	v_mfma_f32_16x16x32_bf16 v[46:49], v[134:137], v[174:177], v[46:49]
	v_mfma_f32_16x16x32_bf16 v[42:45], v[142:145], v[174:177], v[42:45]
	v_mfma_f32_16x16x32_bf16 v[30:33], v[134:137], v[200:203], v[30:33]
	v_mfma_f32_16x16x32_bf16 v[26:29], v[142:145], v[200:203], v[26:29]
	v_mfma_f32_16x16x32_bf16 v[14:17], v[134:137], v[216:219], v[14:17]
	v_mfma_f32_16x16x32_bf16 v[10:13], v[142:145], v[216:219], v[10:13]
	s_setprio 0
	s_setprio 1
	v_mfma_f32_16x16x32_bf16 v[54:57], v[146:149], v[162:165], v[54:57]
	v_mfma_f32_16x16x32_bf16 v[50:53], v[154:157], v[162:165], v[50:53]
	v_mfma_f32_16x16x32_bf16 v[38:41], v[146:149], v[170:173], v[38:41]
	v_mfma_f32_16x16x32_bf16 v[34:37], v[154:157], v[170:173], v[34:37]
	v_mfma_f32_16x16x32_bf16 v[22:25], v[146:149], v[196:199], v[22:25]
	v_mfma_f32_16x16x32_bf16 v[18:21], v[154:157], v[196:199], v[18:21]
	v_mfma_f32_16x16x32_bf16 v[6:9], v[146:149], v[212:215], v[6:9]
	v_mfma_f32_16x16x32_bf16 v[2:5], v[154:157], v[212:215], v[2:5]
	v_mfma_f32_16x16x32_bf16 v[54:57], v[150:153], v[166:169], v[54:57]
	v_mfma_f32_16x16x32_bf16 v[50:53], v[158:161], v[166:169], v[50:53]
	v_mfma_f32_16x16x32_bf16 v[38:41], v[150:153], v[174:177], v[38:41]
	v_mfma_f32_16x16x32_bf16 v[34:37], v[158:161], v[174:177], v[34:37]
	v_mfma_f32_16x16x32_bf16 v[22:25], v[150:153], v[200:203], v[22:25]
	v_mfma_f32_16x16x32_bf16 v[18:21], v[158:161], v[200:203], v[18:21]
	v_mfma_f32_16x16x32_bf16 v[6:9], v[150:153], v[216:219], v[6:9]
	v_mfma_f32_16x16x32_bf16 v[2:5], v[158:161], v[216:219], v[2:5]
	s_barrier
	s_setprio 0
	s_add_i32 s83, s83, 2
	s_add_u32 s12, s12, 0x100
	s_addc_u32 s13, s13, 0
	s_add_u32 s81, s81, 0x100
	s_addc_u32 s82, s82, 0
	s_cmpk_gt_u32 s83, 0x55

.LBB0_466:
	ds_read_b128 v[78:81], v204
	ds_read_b128 v[138:141], v204 offset:1024
	ds_read_b128 v[142:145], v204 offset:2048
	ds_read_b128 v[146:149], v204 offset:3072
	ds_read_b128 v[170:173], v205
	ds_read_b128 v[174:177], v205 offset:1024
	ds_read_b128 v[180:183], v205 offset:2048
	ds_read_b128 v[210:213], v205 offset:3072
	ds_read_b128 v[214:217], v206
	ds_read_b128 v[218:221], v206 offset:1024
	ds_read_b128 v[222:225], v206 offset:2048
	ds_read_b128 v[226:229], v206 offset:3072
	ds_read_b128 v[230:233], v206 offset:4096
	ds_read_b128 v[234:237], v206 offset:5120
	ds_read_b128 v[238:241], v206 offset:6144
	ds_read_b128 v[242:245], v206 offset:7168
	s_add_i32 s22, s22, 1
	s_mul_i32 s4, s22, s42
	s_mul_hi_u32 s5, s22, s33
	s_add_i32 s5, s5, s4
	s_mul_i32 s4, s22, s33
	s_add_u32 s70, s4, s88
	s_addc_u32 s71, s5, s43
	v_mov_b64_e32 v[2:3], 0x1480
	v_cmp_lt_i64_e64 s[4:5], s[70:71], v[2:3]
	v_mov_b64_e32 v[2:3], 0x147f
	v_cmp_gt_i64_e32 vcc, s[70:71], v[2:3]
	s_mov_b32 s29, s10
	s_cbranch_vccnz .LBB0_468
	s_ashr_i32 s10, s70, 31
	s_lshr_b32 s10, s10, 29
	s_add_i32 s10, s70, s10
	s_ashr_i32 s11, s10, 3
	s_and_b32 s10, s10, -8
	s_sub_i32 s10, s70, s10
	s_cmp_lt_i32 s10, 0
	s_movk_i32 s68, 0x291
	s_cselect_b32 s68, s68, 0x290
	s_mul_i32 s10, s10, s68
	s_add_i32 s10, s10, s11
	s_mul_hi_i32 s11, s10, 0x63e7063f
	s_lshr_b32 s68, s11, 31
	s_ashr_i32 s11, s11, 7
	s_add_i32 s11, s11, s68
	s_lshl_b32 s69, s11, 3
	s_mulk_i32 s11, 0x148
	s_sub_i32 s10, s10, s11
	s_lshr_b32 s68, s10, 3
	s_and_b32 s10, s10, 7
	s_add_i32 s10, s69, s10
.LBB0_468:
	s_ashr_i32 s11, s10, 31
	s_lshl_b64 s[70:71], s[10:11], 20
	s_add_u32 s70, s89, s70
	s_addc_u32 s71, s90, s71
	s_and_b64 s[72:73], s[4:5], exec
	s_cselect_b32 s11, s71, s1
	s_cselect_b32 s76, s70, s0
	s_ashr_i32 s69, s68, 31
	s_lshl_b64 s[72:73], s[68:69], 20
	s_add_u32 s72, s91, s72
	s_addc_u32 s73, s92, s73
	s_and_b64 s[74:75], s[4:5], exec
	s_cselect_b32 s69, s73, s9
	s_cselect_b32 s77, s72, s8
	s_add_u32 s0, s0, 0x80080
	s_addc_u32 s1, s1, 0
	s_add_u32 s78, s8, 0x100
	s_addc_u32 s79, s9, 0
	s_mov_b32 s80, -2
	s_add_u32 s8, s0, 0xfff80080
	s_addc_u32 s9, s1, -1
	s_cmp_eq_u32 s80, 28
	s_cselect_b32 s75, s11, s9
	s_cselect_b32 s74, s76, s8
	s_cselect_b32 s9, s69, s79
	s_cselect_b32 s8, s77, s78
	s_add_i32 m0, s94, 0xc000
	s_nop 0
	global_load_lds_dwordx4 v162, s[0:1]
	s_add_i32 m0, s94, 0xe000
	s_nop 0
	global_load_lds_dwordx4 v164, s[0:1]
	s_waitcnt vmcnt(8)
	s_waitcnt lgkmcnt(0)
	s_setprio 1
	s_barrier
	v_mfma_f32_16x16x32_bf16 v[66:69], v[78:81], v[214:217], 0
	v_mfma_f32_16x16x32_bf16 v[62:65], v[142:145], v[214:217], 0
	v_mfma_f32_16x16x32_bf16 v[58:61], v[78:81], v[222:225], 0
	v_mfma_f32_16x16x32_bf16 v[54:57], v[142:145], v[222:225], 0
	v_mfma_f32_16x16x32_bf16 v[46:49], v[78:81], v[230:233], 0
	v_mfma_f32_16x16x32_bf16 v[42:45], v[142:145], v[230:233], 0
	v_mfma_f32_16x16x32_bf16 v[38:41], v[78:81], v[238:241], 0
	v_mfma_f32_16x16x32_bf16 v[34:37], v[142:145], v[238:241], 0
	v_mfma_f32_16x16x32_bf16 v[66:69], v[138:141], v[218:221], v[66:69]
	v_mfma_f32_16x16x32_bf16 v[62:65], v[146:149], v[218:221], v[62:65]
	v_mfma_f32_16x16x32_bf16 v[58:61], v[138:141], v[226:229], v[58:61]
	v_mfma_f32_16x16x32_bf16 v[54:57], v[146:149], v[226:229], v[54:57]
	v_mfma_f32_16x16x32_bf16 v[46:49], v[138:141], v[234:237], v[46:49]
	v_mfma_f32_16x16x32_bf16 v[42:45], v[146:149], v[234:237], v[42:45]
	v_mfma_f32_16x16x32_bf16 v[38:41], v[138:141], v[242:245], v[38:41]
	v_mfma_f32_16x16x32_bf16 v[34:37], v[146:149], v[242:245], v[34:37]
	s_setprio 0
	s_setprio 1
	v_mfma_f32_16x16x32_bf16 v[134:137], v[170:173], v[214:217], 0
	v_mfma_f32_16x16x32_bf16 v[130:133], v[180:183], v[214:217], 0
	v_mfma_f32_16x16x32_bf16 v[126:129], v[170:173], v[222:225], 0
	v_mfma_f32_16x16x32_bf16 v[122:125], v[180:183], v[222:225], 0
	v_mfma_f32_16x16x32_bf16 v[118:121], v[170:173], v[230:233], 0
	v_mfma_f32_16x16x32_bf16 v[114:117], v[180:183], v[230:233], 0
	v_mfma_f32_16x16x32_bf16 v[110:113], v[170:173], v[238:241], 0
	v_mfma_f32_16x16x32_bf16 v[106:109], v[180:183], v[238:241], 0
	v_mfma_f32_16x16x32_bf16 v[134:137], v[174:177], v[218:221], v[134:137]
	v_mfma_f32_16x16x32_bf16 v[130:133], v[210:213], v[218:221], v[130:133]
	v_mfma_f32_16x16x32_bf16 v[126:129], v[174:177], v[226:229], v[126:129]
	v_mfma_f32_16x16x32_bf16 v[122:125], v[210:213], v[226:229], v[122:125]
	v_mfma_f32_16x16x32_bf16 v[118:121], v[174:177], v[234:237], v[118:121]
	v_mfma_f32_16x16x32_bf16 v[114:117], v[210:213], v[234:237], v[114:117]
	v_mfma_f32_16x16x32_bf16 v[110:113], v[174:177], v[242:245], v[110:113]
	v_mfma_f32_16x16x32_bf16 v[106:109], v[210:213], v[242:245], v[106:109]
	s_barrier
	s_setprio 0
	s_add_i32 s81, s53, s93
	s_add_u32 s98, s8, 0x80
	s_addc_u32 s99, s9, 0
	s_mov_b32 m0, s81
	ds_read_b128 v[214:217], v206 offset:16384
	ds_read_b128 v[218:221], v206 offset:17408
	ds_read_b128 v[222:225], v206 offset:18432
	ds_read_b128 v[226:229], v206 offset:19456
	ds_read_b128 v[230:233], v206 offset:20480
	ds_read_b128 v[234:237], v206 offset:21504
	ds_read_b128 v[238:241], v206 offset:22528
	ds_read_b128 v[242:245], v206 offset:23552
	global_load_lds_dwordx4 v152, s[8:9]
	s_add_i32 m0, s81, 0x2000
	s_add_u32 s82, s8, 0x80000
	s_addc_u32 s83, s9, 0
	s_add_i32 s81, s54, s93
	global_load_lds_dwordx4 v156, s[8:9]
	s_mov_b32 m0, s81
	s_nop 0
	global_load_lds_dwordx4 v152, s[82:83]
	s_add_i32 m0, s81, 0x2000
	s_nop 0
	global_load_lds_dwordx4 v156, s[82:83]
	s_add_u32 s100, s74, 0x80
	s_addc_u32 s101, s75, 0
	s_mov_b32 m0, s94
	s_nop 0
	global_load_lds_dwordx4 v150, s[74:75]
	s_mov_b32 m0, s95
	s_nop 0
	global_load_lds_dwordx4 v154, s[74:75]
	s_waitcnt vmcnt(8)
	s_waitcnt lgkmcnt(0)
	s_setprio 1
	s_barrier
	v_mfma_f32_16x16x32_bf16 v[30:33], v[78:81], v[214:217], 0
	v_mfma_f32_16x16x32_bf16 v[26:29], v[142:145], v[214:217], 0
	v_mfma_f32_16x16x32_bf16 v[22:25], v[78:81], v[222:225], 0
	v_mfma_f32_16x16x32_bf16 v[18:21], v[142:145], v[222:225], 0
	v_mfma_f32_16x16x32_bf16 v[14:17], v[78:81], v[230:233], 0
	v_mfma_f32_16x16x32_bf16 v[10:13], v[142:145], v[230:233], 0
	v_mfma_f32_16x16x32_bf16 v[6:9], v[78:81], v[238:241], 0
	v_mfma_f32_16x16x32_bf16 v[2:5], v[142:145], v[238:241], 0
	v_mfma_f32_16x16x32_bf16 v[30:33], v[138:141], v[218:221], v[30:33]
	v_mfma_f32_16x16x32_bf16 v[26:29], v[146:149], v[218:221], v[26:29]
	v_mfma_f32_16x16x32_bf16 v[22:25], v[138:141], v[226:229], v[22:25]
	v_mfma_f32_16x16x32_bf16 v[18:21], v[146:149], v[226:229], v[18:21]
	v_mfma_f32_16x16x32_bf16 v[14:17], v[138:141], v[234:237], v[14:17]
	v_mfma_f32_16x16x32_bf16 v[10:13], v[146:149], v[234:237], v[10:13]
	v_mfma_f32_16x16x32_bf16 v[6:9], v[138:141], v[242:245], v[6:9]
	v_mfma_f32_16x16x32_bf16 v[2:5], v[146:149], v[242:245], v[2:5]
	s_setprio 0
	s_setprio 1
	v_mfma_f32_16x16x32_bf16 v[98:101], v[180:183], v[214:217], 0
	v_mfma_f32_16x16x32_bf16 v[94:97], v[170:173], v[222:225], 0
	v_mfma_f32_16x16x32_bf16 v[90:93], v[180:183], v[222:225], 0
	v_mfma_f32_16x16x32_bf16 v[86:89], v[170:173], v[230:233], 0
	v_mfma_f32_16x16x32_bf16 v[82:85], v[180:183], v[230:233], 0
	v_mfma_f32_16x16x32_bf16 v[74:77], v[170:173], v[238:241], 0
	v_mfma_f32_16x16x32_bf16 v[70:73], v[180:183], v[238:241], 0
	v_mfma_f32_16x16x32_bf16 v[78:81], v[170:173], v[214:217], 0
	v_mfma_f32_16x16x32_bf16 v[98:101], v[210:213], v[218:221], v[98:101]
	v_mfma_f32_16x16x32_bf16 v[94:97], v[174:177], v[226:229], v[94:97]
	v_mfma_f32_16x16x32_bf16 v[90:93], v[210:213], v[226:229], v[90:93]
	v_mfma_f32_16x16x32_bf16 v[86:89], v[174:177], v[234:237], v[86:89]
	v_mfma_f32_16x16x32_bf16 v[82:85], v[210:213], v[234:237], v[82:85]
	v_mfma_f32_16x16x32_bf16 v[74:77], v[174:177], v[242:245], v[74:77]
	v_mfma_f32_16x16x32_bf16 v[70:73], v[210:213], v[242:245], v[70:73]
	v_mfma_f32_16x16x32_bf16 v[78:81], v[174:177], v[218:221], v[78:81]
	s_barrier
	s_setprio 0
	s_add_i32 s81, 0, 0x18000
	s_add_i32 s82, 0, 0x1c000
	ds_read_b128 v[102:105], v204 offset:32768
	ds_read_b128 v[138:141], v204 offset:33792
	ds_read_b128 v[142:145], v204 offset:34816
	ds_read_b128 v[146:149], v204 offset:35840
	ds_read_b128 v[170:173], v205 offset:32768
	ds_read_b128 v[174:177], v205 offset:33792
	ds_read_b128 v[180:183], v205 offset:34816
	ds_read_b128 v[210:213], v205 offset:35840
	s_add_u32 s74, s74, 0x80000
	s_addc_u32 s75, s75, 0
	s_mov_b32 m0, s96
	ds_read_b128 v[214:217], v206 offset:32768
	ds_read_b128 v[218:221], v206 offset:33792
	ds_read_b128 v[222:225], v206 offset:34816
	ds_read_b128 v[226:229], v206 offset:35840
	ds_read_b128 v[230:233], v206 offset:36864
	ds_read_b128 v[234:237], v206 offset:37888
	ds_read_b128 v[238:241], v206 offset:38912
	ds_read_b128 v[242:245], v206 offset:39936
	global_load_lds_dwordx4 v150, s[74:75]
	s_mov_b32 m0, s97
	s_nop 0
	global_load_lds_dwordx4 v154, s[74:75]
	s_waitcnt vmcnt(8)
	s_waitcnt lgkmcnt(0)
	s_setprio 1
	s_barrier
	v_mfma_f32_16x16x32_bf16 v[66:69], v[102:105], v[214:217], v[66:69]
	v_mfma_f32_16x16x32_bf16 v[62:65], v[142:145], v[214:217], v[62:65]
	v_mfma_f32_16x16x32_bf16 v[58:61], v[102:105], v[222:225], v[58:61]
	v_mfma_f32_16x16x32_bf16 v[54:57], v[142:145], v[222:225], v[54:57]
	v_mfma_f32_16x16x32_bf16 v[46:49], v[102:105], v[230:233], v[46:49]
	v_mfma_f32_16x16x32_bf16 v[42:45], v[142:145], v[230:233], v[42:45]
	v_mfma_f32_16x16x32_bf16 v[38:41], v[102:105], v[238:241], v[38:41]
	v_mfma_f32_16x16x32_bf16 v[34:37], v[142:145], v[238:241], v[34:37]
	v_mfma_f32_16x16x32_bf16 v[66:69], v[138:141], v[218:221], v[66:69]
	v_mfma_f32_16x16x32_bf16 v[62:65], v[146:149], v[218:221], v[62:65]
	v_mfma_f32_16x16x32_bf16 v[58:61], v[138:141], v[226:229], v[58:61]
	v_mfma_f32_16x16x32_bf16 v[54:57], v[146:149], v[226:229], v[54:57]
	v_mfma_f32_16x16x32_bf16 v[46:49], v[138:141], v[234:237], v[46:49]
	v_mfma_f32_16x16x32_bf16 v[42:45], v[146:149], v[234:237], v[42:45]
	v_mfma_f32_16x16x32_bf16 v[38:41], v[138:141], v[242:245], v[38:41]
	v_mfma_f32_16x16x32_bf16 v[34:37], v[146:149], v[242:245], v[34:37]
	s_setprio 0
	s_setprio 1
	v_mfma_f32_16x16x32_bf16 v[134:137], v[170:173], v[214:217], v[134:137]
	v_mfma_f32_16x16x32_bf16 v[130:133], v[180:183], v[214:217], v[130:133]
	v_mfma_f32_16x16x32_bf16 v[126:129], v[170:173], v[222:225], v[126:129]
	v_mfma_f32_16x16x32_bf16 v[122:125], v[180:183], v[222:225], v[122:125]
	v_mfma_f32_16x16x32_bf16 v[118:121], v[170:173], v[230:233], v[118:121]
	v_mfma_f32_16x16x32_bf16 v[114:117], v[180:183], v[230:233], v[114:117]
	v_mfma_f32_16x16x32_bf16 v[110:113], v[170:173], v[238:241], v[110:113]
	v_mfma_f32_16x16x32_bf16 v[106:109], v[180:183], v[238:241], v[106:109]
	v_mfma_f32_16x16x32_bf16 v[134:137], v[174:177], v[218:221], v[134:137]
	v_mfma_f32_16x16x32_bf16 v[130:133], v[210:213], v[218:221], v[130:133]
	v_mfma_f32_16x16x32_bf16 v[126:129], v[174:177], v[226:229], v[126:129]
	v_mfma_f32_16x16x32_bf16 v[122:125], v[210:213], v[226:229], v[122:125]
	v_mfma_f32_16x16x32_bf16 v[118:121], v[174:177], v[234:237], v[118:121]
	v_mfma_f32_16x16x32_bf16 v[114:117], v[210:213], v[234:237], v[114:117]
	v_mfma_f32_16x16x32_bf16 v[110:113], v[174:177], v[242:245], v[110:113]
	v_mfma_f32_16x16x32_bf16 v[106:109], v[210:213], v[242:245], v[106:109]
	s_barrier
	s_setprio 0
	s_add_i32 s74, s81, s93
	s_mov_b32 m0, s74
	ds_read_b128 v[214:217], v206 offset:49152
	ds_read_b128 v[218:221], v206 offset:50176
	ds_read_b128 v[222:225], v206 offset:51200
	ds_read_b128 v[226:229], v206 offset:52224
	ds_read_b128 v[230:233], v206 offset:53248
	ds_read_b128 v[234:237], v206 offset:54272
	ds_read_b128 v[238:241], v206 offset:55296
	ds_read_b128 v[242:245], v206 offset:56320
	global_load_lds_dwordx4 v152, s[98:99]
	s_add_i32 m0, s74, 0x2000
	s_add_u32 s8, s8, 0x80080
	s_addc_u32 s9, s9, 0
	s_add_i32 s74, s82, s93
	global_load_lds_dwordx4 v156, s[98:99]
	s_mov_b32 m0, s74
	s_nop 0
	global_load_lds_dwordx4 v152, s[8:9]
	s_add_i32 m0, s74, 0x2000
	s_nop 0
	global_load_lds_dwordx4 v156, s[8:9]
	s_mov_b32 m0, s85
	s_nop 0
	global_load_lds_dwordx4 v150, s[100:101]
	s_mov_b32 m0, s18
	s_nop 0
	global_load_lds_dwordx4 v154, s[100:101]
	s_waitcnt vmcnt(8)
	s_waitcnt lgkmcnt(0)
	s_setprio 1
	s_barrier
	v_mfma_f32_16x16x32_bf16 v[30:33], v[102:105], v[214:217], v[30:33]
	v_mfma_f32_16x16x32_bf16 v[26:29], v[142:145], v[214:217], v[26:29]
	v_mfma_f32_16x16x32_bf16 v[22:25], v[102:105], v[222:225], v[22:25]
	v_mfma_f32_16x16x32_bf16 v[18:21], v[142:145], v[222:225], v[18:21]
	v_mfma_f32_16x16x32_bf16 v[14:17], v[102:105], v[230:233], v[14:17]
	v_mfma_f32_16x16x32_bf16 v[10:13], v[142:145], v[230:233], v[10:13]
	v_mfma_f32_16x16x32_bf16 v[6:9], v[102:105], v[238:241], v[6:9]
	v_mfma_f32_16x16x32_bf16 v[2:5], v[142:145], v[238:241], v[2:5]
	v_mfma_f32_16x16x32_bf16 v[30:33], v[138:141], v[218:221], v[30:33]
	v_mfma_f32_16x16x32_bf16 v[26:29], v[146:149], v[218:221], v[26:29]
	v_mfma_f32_16x16x32_bf16 v[22:25], v[138:141], v[226:229], v[22:25]
	v_mfma_f32_16x16x32_bf16 v[18:21], v[146:149], v[226:229], v[18:21]
	v_mfma_f32_16x16x32_bf16 v[14:17], v[138:141], v[234:237], v[14:17]
	v_mfma_f32_16x16x32_bf16 v[10:13], v[146:149], v[234:237], v[10:13]
	v_mfma_f32_16x16x32_bf16 v[6:9], v[138:141], v[242:245], v[6:9]
	v_mfma_f32_16x16x32_bf16 v[2:5], v[146:149], v[242:245], v[2:5]
	s_setprio 0
	s_setprio 1
	v_mfma_f32_16x16x32_bf16 v[78:81], v[170:173], v[214:217], v[78:81]
	v_mfma_f32_16x16x32_bf16 v[102:105], v[174:177], v[218:221], v[78:81]
	v_mfma_f32_16x16x32_bf16 v[78:81], v[180:183], v[214:217], v[98:101]
	v_mfma_f32_16x16x32_bf16 v[98:101], v[210:213], v[218:221], v[78:81]
	v_mfma_f32_16x16x32_bf16 v[78:81], v[170:173], v[222:225], v[94:97]
	v_mfma_f32_16x16x32_bf16 v[94:97], v[174:177], v[226:229], v[78:81]
	v_mfma_f32_16x16x32_bf16 v[78:81], v[180:183], v[222:225], v[90:93]
	v_mfma_f32_16x16x32_bf16 v[90:93], v[210:213], v[226:229], v[78:81]
	v_mfma_f32_16x16x32_bf16 v[78:81], v[170:173], v[230:233], v[86:89]
	v_mfma_f32_16x16x32_bf16 v[86:89], v[174:177], v[234:237], v[78:81]
	v_mfma_f32_16x16x32_bf16 v[78:81], v[180:183], v[230:233], v[82:85]
	v_mfma_f32_16x16x32_bf16 v[74:77], v[170:173], v[238:241], v[74:77]
	v_mfma_f32_16x16x32_bf16 v[70:73], v[180:183], v[238:241], v[70:73]
	v_mfma_f32_16x16x32_bf16 v[82:85], v[210:213], v[234:237], v[78:81]
	v_mfma_f32_16x16x32_bf16 v[74:77], v[174:177], v[242:245], v[74:77]
	v_mfma_f32_16x16x32_bf16 v[70:73], v[210:213], v[242:245], v[70:73]
	s_barrier
	s_setprio 0
	s_add_i32 s80, s80, 2
	s_add_u32 s0, s0, 0x100
	s_addc_u32 s1, s1, 0
	s_add_u32 s78, s78, 0x100
	s_addc_u32 s79, s79, 0
	s_cmp_gt_u32 s80, 29

.LBB0_694:
	ds_read_b128 v[144:147], v141
	ds_read_b128 v[158:161], v141 offset:1024
	ds_read_b128 v[162:165], v141 offset:2048
	ds_read_b128 v[166:169], v141 offset:3072
	ds_read_b128 v[170:173], v142
	ds_read_b128 v[174:177], v142 offset:1024
	ds_read_b128 v[180:183], v142 offset:2048
	ds_read_b128 v[190:193], v142 offset:3072
	ds_read_b128 v[194:197], v143
	ds_read_b128 v[198:201], v143 offset:1024
	ds_read_b128 v[202:205], v143 offset:2048
	ds_read_b128 v[206:209], v143 offset:3072
	ds_read_b128 v[210:213], v143 offset:4096
	ds_read_b128 v[214:217], v143 offset:5120
	ds_read_b128 v[218:221], v143 offset:6144
	ds_read_b128 v[222:225], v143 offset:7168
	s_add_i32 s64, s64, 1
	s_mul_i32 s16, s64, s67
	s_mul_hi_u32 s17, s64, s33
	s_add_i32 s17, s17, s16
	s_mul_i32 s16, s64, s33
	s_add_u32 s40, s16, s22
	s_addc_u32 s41, s17, s23
	v_cmp_gt_i64_e64 s[42:43], s[40:41], 31
	v_cmp_lt_i64_e64 s[16:17], s[40:41], 32
	s_and_b64 vcc, exec, s[42:43]
	s_cbranch_vccnz .LBB0_700
	s_ashr_i32 s34, s40, 31
	s_lshr_b32 s34, s34, 29
	s_add_i32 s36, s40, s34
	s_and_b32 s34, s36, -8
	s_sub_i32 s37, s40, s34
	s_cmp_gt_i32 s37, -1
	s_mov_b64 s[34:35], -1
	s_cbranch_scc0 .LBB0_697
	s_lshl_b32 s40, s37, 2
	s_mov_b64 s[34:35], 0

.LBB0_700:
	s_ashr_i32 s37, s36, 31
	s_lshl_b64 s[40:41], s[36:37], 20
	s_add_u32 s40, s18, s40
	s_addc_u32 s41, s19, s41
	s_and_b64 s[42:43], s[16:17], exec
	s_cselect_b32 s37, s41, s55
	s_cselect_b32 s75, s40, s54
	s_ashr_i32 s35, s34, 31
	s_lshl_b64 s[42:43], s[34:35], 20
	s_add_u32 s42, s28, s42
	s_addc_u32 s43, s29, s43
	s_and_b64 s[58:59], s[16:17], exec
	s_cselect_b32 s35, s43, s57
	s_cselect_b32 s76, s42, s56
	s_add_u32 s54, s54, 0x80080
	s_addc_u32 s55, s55, 0
	s_add_u32 s77, s56, 0x100
	s_addc_u32 s78, s57, 0
	s_mov_b32 s79, -2
	s_add_u32 s56, s54, 0xfff80080
	s_addc_u32 s57, s55, -1
	s_cmp_eq_u32 s79, 28
	s_cselect_b32 s59, s37, s57
	s_cselect_b32 s58, s75, s56
	s_cselect_b32 s57, s35, s78
	s_cselect_b32 s56, s76, s77
	s_add_i32 m0, s53, 0xc000
	s_nop 0
	global_load_lds_dwordx4 v130, s[54:55]
	s_add_i32 m0, s53, 0xe000
	s_nop 0
	global_load_lds_dwordx4 v132, s[54:55]
	s_waitcnt vmcnt(8)
	s_waitcnt lgkmcnt(0)
	s_setprio 1
	s_barrier
	v_mfma_f32_16x16x32_bf16 v[126:129], v[144:147], v[194:197], 0
	v_mfma_f32_16x16x32_bf16 v[122:125], v[162:165], v[194:197], 0
	v_mfma_f32_16x16x32_bf16 v[114:117], v[144:147], v[202:205], 0
	v_mfma_f32_16x16x32_bf16 v[106:109], v[162:165], v[202:205], 0
	v_mfma_f32_16x16x32_bf16 v[98:101], v[144:147], v[210:213], 0
	v_mfma_f32_16x16x32_bf16 v[90:93], v[162:165], v[210:213], 0
	v_mfma_f32_16x16x32_bf16 v[82:85], v[144:147], v[218:221], 0
	v_mfma_f32_16x16x32_bf16 v[74:77], v[162:165], v[218:221], 0
	v_mfma_f32_16x16x32_bf16 v[126:129], v[158:161], v[198:201], v[126:129]
	v_mfma_f32_16x16x32_bf16 v[122:125], v[166:169], v[198:201], v[122:125]
	v_mfma_f32_16x16x32_bf16 v[114:117], v[158:161], v[206:209], v[114:117]
	v_mfma_f32_16x16x32_bf16 v[106:109], v[166:169], v[206:209], v[106:109]
	v_mfma_f32_16x16x32_bf16 v[98:101], v[158:161], v[214:217], v[98:101]
	v_mfma_f32_16x16x32_bf16 v[90:93], v[166:169], v[214:217], v[90:93]
	v_mfma_f32_16x16x32_bf16 v[82:85], v[158:161], v[222:225], v[82:85]
	v_mfma_f32_16x16x32_bf16 v[74:77], v[166:169], v[222:225], v[74:77]
	s_setprio 0
	s_setprio 1
	v_mfma_f32_16x16x32_bf16 v[118:121], v[170:173], v[194:197], 0
	v_mfma_f32_16x16x32_bf16 v[110:113], v[180:183], v[194:197], 0
	v_mfma_f32_16x16x32_bf16 v[102:105], v[170:173], v[202:205], 0
	v_mfma_f32_16x16x32_bf16 v[94:97], v[180:183], v[202:205], 0
	v_mfma_f32_16x16x32_bf16 v[86:89], v[170:173], v[210:213], 0
	v_mfma_f32_16x16x32_bf16 v[78:81], v[180:183], v[210:213], 0
	v_mfma_f32_16x16x32_bf16 v[70:73], v[170:173], v[218:221], 0
	v_mfma_f32_16x16x32_bf16 v[66:69], v[180:183], v[218:221], 0
	v_mfma_f32_16x16x32_bf16 v[118:121], v[174:177], v[198:201], v[118:121]
	v_mfma_f32_16x16x32_bf16 v[110:113], v[190:193], v[198:201], v[110:113]
	v_mfma_f32_16x16x32_bf16 v[102:105], v[174:177], v[206:209], v[102:105]
	v_mfma_f32_16x16x32_bf16 v[94:97], v[190:193], v[206:209], v[94:97]
	v_mfma_f32_16x16x32_bf16 v[86:89], v[174:177], v[214:217], v[86:89]
	v_mfma_f32_16x16x32_bf16 v[78:81], v[190:193], v[214:217], v[78:81]
	v_mfma_f32_16x16x32_bf16 v[70:73], v[174:177], v[222:225], v[70:73]
	v_mfma_f32_16x16x32_bf16 v[66:69], v[190:193], v[222:225], v[66:69]
	s_barrier
	s_setprio 0
	s_add_i32 s80, s68, s60
	s_add_u32 s98, s56, 0x80
	s_addc_u32 s99, s57, 0
	s_mov_b32 m0, s80
	ds_read_b128 v[194:197], v143 offset:16384
	ds_read_b128 v[198:201], v143 offset:17408
	ds_read_b128 v[202:205], v143 offset:18432
	ds_read_b128 v[206:209], v143 offset:19456
	ds_read_b128 v[210:213], v143 offset:20480
	ds_read_b128 v[214:217], v143 offset:21504
	ds_read_b128 v[218:221], v143 offset:22528
	ds_read_b128 v[222:225], v143 offset:23552
	global_load_lds_dwordx4 v152, s[56:57]
	s_add_i32 m0, s80, 0x2000
	s_add_u32 s80, s56, 0x80000
	s_addc_u32 s81, s57, 0
	s_add_i32 s82, s69, s60
	global_load_lds_dwordx4 v156, s[56:57]
	s_mov_b32 m0, s82
	s_nop 0
	global_load_lds_dwordx4 v152, s[80:81]
	s_add_i32 m0, s82, 0x2000
	s_nop 0
	global_load_lds_dwordx4 v156, s[80:81]
	s_add_u32 s100, s58, 0x80
	s_addc_u32 s101, s59, 0
	s_mov_b32 m0, s53
	s_nop 0
	global_load_lds_dwordx4 v150, s[58:59]
	s_mov_b32 m0, s61
	s_nop 0
	global_load_lds_dwordx4 v154, s[58:59]
	s_waitcnt vmcnt(8)
	s_waitcnt lgkmcnt(0)
	s_setprio 1
	s_barrier
	v_mfma_f32_16x16x32_bf16 v[62:65], v[144:147], v[194:197], 0
	v_mfma_f32_16x16x32_bf16 v[58:61], v[162:165], v[194:197], 0
	v_mfma_f32_16x16x32_bf16 v[50:53], v[144:147], v[202:205], 0
	v_mfma_f32_16x16x32_bf16 v[42:45], v[162:165], v[202:205], 0
	v_mfma_f32_16x16x32_bf16 v[34:37], v[144:147], v[210:213], 0
	v_mfma_f32_16x16x32_bf16 v[26:29], v[162:165], v[210:213], 0
	v_mfma_f32_16x16x32_bf16 v[18:21], v[144:147], v[218:221], 0
	v_mfma_f32_16x16x32_bf16 v[10:13], v[162:165], v[218:221], 0
	v_mfma_f32_16x16x32_bf16 v[62:65], v[158:161], v[198:201], v[62:65]
	v_mfma_f32_16x16x32_bf16 v[58:61], v[166:169], v[198:201], v[58:61]
	v_mfma_f32_16x16x32_bf16 v[50:53], v[158:161], v[206:209], v[50:53]
	v_mfma_f32_16x16x32_bf16 v[42:45], v[166:169], v[206:209], v[42:45]
	v_mfma_f32_16x16x32_bf16 v[34:37], v[158:161], v[214:217], v[34:37]
	v_mfma_f32_16x16x32_bf16 v[26:29], v[166:169], v[214:217], v[26:29]
	v_mfma_f32_16x16x32_bf16 v[18:21], v[158:161], v[222:225], v[18:21]
	v_mfma_f32_16x16x32_bf16 v[10:13], v[166:169], v[222:225], v[10:13]
	s_setprio 0
	s_setprio 1
	v_mfma_f32_16x16x32_bf16 v[54:57], v[170:173], v[194:197], 0
	v_mfma_f32_16x16x32_bf16 v[46:49], v[180:183], v[194:197], 0
	v_mfma_f32_16x16x32_bf16 v[38:41], v[170:173], v[202:205], 0
	v_mfma_f32_16x16x32_bf16 v[30:33], v[180:183], v[202:205], 0
	v_mfma_f32_16x16x32_bf16 v[22:25], v[170:173], v[210:213], 0
	v_mfma_f32_16x16x32_bf16 v[14:17], v[180:183], v[210:213], 0
	v_mfma_f32_16x16x32_bf16 v[6:9], v[170:173], v[218:221], 0
	v_mfma_f32_16x16x32_bf16 v[2:5], v[180:183], v[218:221], 0
	v_mfma_f32_16x16x32_bf16 v[54:57], v[174:177], v[198:201], v[54:57]
	v_mfma_f32_16x16x32_bf16 v[46:49], v[190:193], v[198:201], v[46:49]
	v_mfma_f32_16x16x32_bf16 v[38:41], v[174:177], v[206:209], v[38:41]
	v_mfma_f32_16x16x32_bf16 v[30:33], v[190:193], v[206:209], v[30:33]
	v_mfma_f32_16x16x32_bf16 v[22:25], v[174:177], v[214:217], v[22:25]
	v_mfma_f32_16x16x32_bf16 v[14:17], v[190:193], v[214:217], v[14:17]
	v_mfma_f32_16x16x32_bf16 v[6:9], v[174:177], v[222:225], v[6:9]
	v_mfma_f32_16x16x32_bf16 v[2:5], v[190:193], v[222:225], v[2:5]
	s_barrier
	s_setprio 0
	s_add_i32 s80, 0, 0x18000
	s_add_i32 s81, 0, 0x1c000
	ds_read_b128 v[144:147], v141 offset:32768
	ds_read_b128 v[158:161], v141 offset:33792
	ds_read_b128 v[162:165], v141 offset:34816
	ds_read_b128 v[166:169], v141 offset:35840
	ds_read_b128 v[170:173], v142 offset:32768
	ds_read_b128 v[174:177], v142 offset:33792
	ds_read_b128 v[180:183], v142 offset:34816
	ds_read_b128 v[190:193], v142 offset:35840
	s_add_u32 s58, s58, 0x80000
	s_addc_u32 s59, s59, 0
	s_mov_b32 m0, s62
	ds_read_b128 v[194:197], v143 offset:32768
	ds_read_b128 v[198:201], v143 offset:33792
	ds_read_b128 v[202:205], v143 offset:34816
	ds_read_b128 v[206:209], v143 offset:35840
	ds_read_b128 v[210:213], v143 offset:36864
	ds_read_b128 v[214:217], v143 offset:37888
	ds_read_b128 v[218:221], v143 offset:38912
	ds_read_b128 v[222:225], v143 offset:39936
	global_load_lds_dwordx4 v150, s[58:59]
	s_mov_b32 m0, s63
	s_nop 0
	global_load_lds_dwordx4 v154, s[58:59]
	s_waitcnt vmcnt(8)
	s_waitcnt lgkmcnt(0)
	s_setprio 1
	s_barrier
	v_mfma_f32_16x16x32_bf16 v[126:129], v[144:147], v[194:197], v[126:129]
	v_mfma_f32_16x16x32_bf16 v[122:125], v[162:165], v[194:197], v[122:125]
	v_mfma_f32_16x16x32_bf16 v[114:117], v[144:147], v[202:205], v[114:117]
	v_mfma_f32_16x16x32_bf16 v[106:109], v[162:165], v[202:205], v[106:109]
	v_mfma_f32_16x16x32_bf16 v[98:101], v[144:147], v[210:213], v[98:101]
	v_mfma_f32_16x16x32_bf16 v[90:93], v[162:165], v[210:213], v[90:93]
	v_mfma_f32_16x16x32_bf16 v[82:85], v[144:147], v[218:221], v[82:85]
	v_mfma_f32_16x16x32_bf16 v[74:77], v[162:165], v[218:221], v[74:77]
	v_mfma_f32_16x16x32_bf16 v[126:129], v[158:161], v[198:201], v[126:129]
	v_mfma_f32_16x16x32_bf16 v[122:125], v[166:169], v[198:201], v[122:125]
	v_mfma_f32_16x16x32_bf16 v[114:117], v[158:161], v[206:209], v[114:117]
	v_mfma_f32_16x16x32_bf16 v[106:109], v[166:169], v[206:209], v[106:109]
	v_mfma_f32_16x16x32_bf16 v[98:101], v[158:161], v[214:217], v[98:101]
	v_mfma_f32_16x16x32_bf16 v[90:93], v[166:169], v[214:217], v[90:93]
	v_mfma_f32_16x16x32_bf16 v[82:85], v[158:161], v[222:225], v[82:85]
	v_mfma_f32_16x16x32_bf16 v[74:77], v[166:169], v[222:225], v[74:77]
	s_setprio 0
	s_setprio 1
	v_mfma_f32_16x16x32_bf16 v[118:121], v[170:173], v[194:197], v[118:121]
	v_mfma_f32_16x16x32_bf16 v[110:113], v[180:183], v[194:197], v[110:113]
	v_mfma_f32_16x16x32_bf16 v[102:105], v[170:173], v[202:205], v[102:105]
	v_mfma_f32_16x16x32_bf16 v[94:97], v[180:183], v[202:205], v[94:97]
	v_mfma_f32_16x16x32_bf16 v[86:89], v[170:173], v[210:213], v[86:89]
	v_mfma_f32_16x16x32_bf16 v[78:81], v[180:183], v[210:213], v[78:81]
	v_mfma_f32_16x16x32_bf16 v[70:73], v[170:173], v[218:221], v[70:73]
	v_mfma_f32_16x16x32_bf16 v[66:69], v[180:183], v[218:221], v[66:69]
	v_mfma_f32_16x16x32_bf16 v[118:121], v[174:177], v[198:201], v[118:121]
	v_mfma_f32_16x16x32_bf16 v[110:113], v[190:193], v[198:201], v[110:113]
	v_mfma_f32_16x16x32_bf16 v[102:105], v[174:177], v[206:209], v[102:105]
	v_mfma_f32_16x16x32_bf16 v[94:97], v[190:193], v[206:209], v[94:97]
	v_mfma_f32_16x16x32_bf16 v[86:89], v[174:177], v[214:217], v[86:89]
	v_mfma_f32_16x16x32_bf16 v[78:81], v[190:193], v[214:217], v[78:81]
	v_mfma_f32_16x16x32_bf16 v[70:73], v[174:177], v[222:225], v[70:73]
	v_mfma_f32_16x16x32_bf16 v[66:69], v[190:193], v[222:225], v[66:69]
	s_barrier
	s_setprio 0
	s_add_i32 s58, s80, s60
	s_mov_b32 m0, s58
	ds_read_b128 v[194:197], v143 offset:49152
	ds_read_b128 v[198:201], v143 offset:50176
	ds_read_b128 v[202:205], v143 offset:51200
	ds_read_b128 v[206:209], v143 offset:52224
	ds_read_b128 v[210:213], v143 offset:53248
	ds_read_b128 v[214:217], v143 offset:54272
	ds_read_b128 v[218:221], v143 offset:55296
	ds_read_b128 v[222:225], v143 offset:56320
	global_load_lds_dwordx4 v152, s[98:99]
	s_add_i32 m0, s58, 0x2000
	s_add_u32 s56, s56, 0x80080
	s_addc_u32 s57, s57, 0
	s_add_i32 s58, s81, s60
	global_load_lds_dwordx4 v156, s[98:99]
	s_mov_b32 m0, s58
	s_nop 0
	global_load_lds_dwordx4 v152, s[56:57]
	s_add_i32 m0, s58, 0x2000
	s_nop 0
	global_load_lds_dwordx4 v156, s[56:57]
	s_mov_b32 m0, s65
	s_nop 0
	global_load_lds_dwordx4 v150, s[100:101]
	s_mov_b32 m0, s66
	s_nop 0
	global_load_lds_dwordx4 v154, s[100:101]
	s_waitcnt vmcnt(8)
	s_waitcnt lgkmcnt(0)
	s_setprio 1
	s_barrier
	v_mfma_f32_16x16x32_bf16 v[62:65], v[144:147], v[194:197], v[62:65]
	v_mfma_f32_16x16x32_bf16 v[58:61], v[162:165], v[194:197], v[58:61]
	v_mfma_f32_16x16x32_bf16 v[50:53], v[144:147], v[202:205], v[50:53]
	v_mfma_f32_16x16x32_bf16 v[42:45], v[162:165], v[202:205], v[42:45]
	v_mfma_f32_16x16x32_bf16 v[34:37], v[144:147], v[210:213], v[34:37]
	v_mfma_f32_16x16x32_bf16 v[26:29], v[162:165], v[210:213], v[26:29]
	v_mfma_f32_16x16x32_bf16 v[18:21], v[144:147], v[218:221], v[18:21]
	v_mfma_f32_16x16x32_bf16 v[10:13], v[162:165], v[218:221], v[10:13]
	v_mfma_f32_16x16x32_bf16 v[62:65], v[158:161], v[198:201], v[62:65]
	v_mfma_f32_16x16x32_bf16 v[58:61], v[166:169], v[198:201], v[58:61]
	v_mfma_f32_16x16x32_bf16 v[50:53], v[158:161], v[206:209], v[50:53]
	v_mfma_f32_16x16x32_bf16 v[42:45], v[166:169], v[206:209], v[42:45]
	v_mfma_f32_16x16x32_bf16 v[34:37], v[158:161], v[214:217], v[34:37]
	v_mfma_f32_16x16x32_bf16 v[26:29], v[166:169], v[214:217], v[26:29]
	v_mfma_f32_16x16x32_bf16 v[18:21], v[158:161], v[222:225], v[18:21]
	v_mfma_f32_16x16x32_bf16 v[10:13], v[166:169], v[222:225], v[10:13]
	s_setprio 0
	s_setprio 1
	v_mfma_f32_16x16x32_bf16 v[54:57], v[170:173], v[194:197], v[54:57]
	v_mfma_f32_16x16x32_bf16 v[46:49], v[180:183], v[194:197], v[46:49]
	v_mfma_f32_16x16x32_bf16 v[38:41], v[170:173], v[202:205], v[38:41]
	v_mfma_f32_16x16x32_bf16 v[30:33], v[180:183], v[202:205], v[30:33]
	v_mfma_f32_16x16x32_bf16 v[22:25], v[170:173], v[210:213], v[22:25]
	v_mfma_f32_16x16x32_bf16 v[14:17], v[180:183], v[210:213], v[14:17]
	v_mfma_f32_16x16x32_bf16 v[6:9], v[170:173], v[218:221], v[6:9]
	v_mfma_f32_16x16x32_bf16 v[2:5], v[180:183], v[218:221], v[2:5]
	v_mfma_f32_16x16x32_bf16 v[54:57], v[174:177], v[198:201], v[54:57]
	v_mfma_f32_16x16x32_bf16 v[46:49], v[190:193], v[198:201], v[46:49]
	v_mfma_f32_16x16x32_bf16 v[38:41], v[174:177], v[206:209], v[38:41]
	v_mfma_f32_16x16x32_bf16 v[30:33], v[190:193], v[206:209], v[30:33]
	v_mfma_f32_16x16x32_bf16 v[22:25], v[174:177], v[214:217], v[22:25]
	v_mfma_f32_16x16x32_bf16 v[14:17], v[190:193], v[214:217], v[14:17]
	v_mfma_f32_16x16x32_bf16 v[6:9], v[174:177], v[222:225], v[6:9]
	v_mfma_f32_16x16x32_bf16 v[2:5], v[190:193], v[222:225], v[2:5]
	s_barrier
	s_setprio 0
	s_add_i32 s79, s79, 2
	s_add_u32 s54, s54, 0x100
	s_addc_u32 s55, s55, 0
	s_add_u32 s77, s77, 0x100
	s_addc_u32 s78, s78, 0
	s_cmp_gt_u32 s79, 29

.LBB0_718:
	ds_read_b128 v[142:145], v139
	ds_read_b128 v[146:149], v139 offset:1024
	ds_read_b128 v[158:161], v139 offset:2048
	ds_read_b128 v[162:165], v139 offset:3072
	ds_read_b128 v[166:169], v140
	ds_read_b128 v[170:173], v140 offset:1024
	ds_read_b128 v[174:177], v140 offset:2048
	ds_read_b128 v[180:183], v140 offset:3072
	ds_read_b128 v[184:187], v141
	ds_read_b128 v[188:191], v141 offset:1024
	ds_read_b128 v[192:195], v141 offset:2048
	ds_read_b128 v[196:199], v141 offset:3072
	ds_read_b128 v[200:203], v141 offset:4096
	ds_read_b128 v[204:207], v141 offset:5120
	ds_read_b128 v[208:211], v141 offset:6144
	ds_read_b128 v[212:215], v141 offset:7168
	s_add_i32 s65, s65, 1
	s_mul_i32 s16, s65, s68
	s_mul_hi_u32 s17, s65, s33
	s_add_i32 s17, s17, s16
	s_mul_i32 s16, s65, s33
	s_add_u32 s40, s16, s28
	s_addc_u32 s41, s17, s29
	v_cmp_gt_i64_e64 s[42:43], s[40:41], 31
	v_cmp_lt_i64_e64 s[16:17], s[40:41], 32
	s_and_b64 vcc, exec, s[42:43]
	s_cbranch_vccnz .LBB0_724
	s_ashr_i32 s34, s40, 31
	s_lshr_b32 s34, s34, 29
	s_add_i32 s36, s40, s34
	s_and_b32 s34, s36, -8
	s_sub_i32 s37, s40, s34
	s_cmp_gt_i32 s37, -1
	s_mov_b64 s[34:35], -1
	s_cbranch_scc0 .LBB0_721
	s_lshl_b32 s40, s37, 2
	s_mov_b64 s[34:35], 0

.LBB0_724:
	s_ashr_i32 s37, s36, 31
	s_lshl_b64 s[40:41], s[36:37], 20
	s_add_u32 s40, s31, s40
	s_addc_u32 s41, s60, s41
	s_and_b64 s[42:43], s[16:17], exec
	s_cselect_b32 s37, s41, s55
	s_cselect_b32 s76, s40, s54
	s_ashr_i32 s35, s34, 31
	s_lshl_b64 s[42:43], s[34:35], 20
	s_add_u32 s42, s18, s42
	s_addc_u32 s43, s19, s43
	s_and_b64 s[58:59], s[16:17], exec
	s_cselect_b32 s35, s43, s57
	s_cselect_b32 s77, s42, s56
	s_add_u32 s54, s54, 0x80080
	s_addc_u32 s55, s55, 0
	s_add_u32 s78, s56, 0x100
	s_addc_u32 s79, s57, 0
	s_mov_b32 s80, -2
	s_add_u32 s56, s54, 0xfff80080
	s_addc_u32 s57, s55, -1
	s_cmp_eq_u32 s80, 28
	s_cselect_b32 s59, s37, s57
	s_cselect_b32 s58, s76, s56
	s_cselect_b32 s57, s35, s79
	s_cselect_b32 s56, s77, s78
	s_add_i32 m0, s53, 0xc000
	s_nop 0
	global_load_lds_dwordx4 v130, s[54:55]
	s_add_i32 m0, s53, 0xe000
	s_nop 0
	global_load_lds_dwordx4 v132, s[54:55]
	s_waitcnt vmcnt(8)
	s_waitcnt lgkmcnt(0)
	s_setprio 1
	s_barrier
	v_mfma_f32_16x16x32_bf16 v[126:129], v[142:145], v[184:187], 0
	v_mfma_f32_16x16x32_bf16 v[122:125], v[158:161], v[184:187], 0
	v_mfma_f32_16x16x32_bf16 v[114:117], v[142:145], v[192:195], 0
	v_mfma_f32_16x16x32_bf16 v[106:109], v[158:161], v[192:195], 0
	v_mfma_f32_16x16x32_bf16 v[98:101], v[142:145], v[200:203], 0
	v_mfma_f32_16x16x32_bf16 v[90:93], v[158:161], v[200:203], 0
	v_mfma_f32_16x16x32_bf16 v[82:85], v[142:145], v[208:211], 0
	v_mfma_f32_16x16x32_bf16 v[74:77], v[158:161], v[208:211], 0
	v_mfma_f32_16x16x32_bf16 v[126:129], v[146:149], v[188:191], v[126:129]
	v_mfma_f32_16x16x32_bf16 v[122:125], v[162:165], v[188:191], v[122:125]
	v_mfma_f32_16x16x32_bf16 v[114:117], v[146:149], v[196:199], v[114:117]
	v_mfma_f32_16x16x32_bf16 v[106:109], v[162:165], v[196:199], v[106:109]
	v_mfma_f32_16x16x32_bf16 v[98:101], v[146:149], v[204:207], v[98:101]
	v_mfma_f32_16x16x32_bf16 v[90:93], v[162:165], v[204:207], v[90:93]
	v_mfma_f32_16x16x32_bf16 v[82:85], v[146:149], v[212:215], v[82:85]
	v_mfma_f32_16x16x32_bf16 v[74:77], v[162:165], v[212:215], v[74:77]
	s_setprio 0
	s_setprio 1
	v_mfma_f32_16x16x32_bf16 v[118:121], v[166:169], v[184:187], 0
	v_mfma_f32_16x16x32_bf16 v[110:113], v[174:177], v[184:187], 0
	v_mfma_f32_16x16x32_bf16 v[102:105], v[166:169], v[192:195], 0
	v_mfma_f32_16x16x32_bf16 v[94:97], v[174:177], v[192:195], 0
	v_mfma_f32_16x16x32_bf16 v[86:89], v[166:169], v[200:203], 0
	v_mfma_f32_16x16x32_bf16 v[78:81], v[174:177], v[200:203], 0
	v_mfma_f32_16x16x32_bf16 v[70:73], v[166:169], v[208:211], 0
	v_mfma_f32_16x16x32_bf16 v[66:69], v[174:177], v[208:211], 0
	v_mfma_f32_16x16x32_bf16 v[118:121], v[170:173], v[188:191], v[118:121]
	v_mfma_f32_16x16x32_bf16 v[110:113], v[180:183], v[188:191], v[110:113]
	v_mfma_f32_16x16x32_bf16 v[102:105], v[170:173], v[196:199], v[102:105]
	v_mfma_f32_16x16x32_bf16 v[94:97], v[180:183], v[196:199], v[94:97]
	v_mfma_f32_16x16x32_bf16 v[86:89], v[170:173], v[204:207], v[86:89]
	v_mfma_f32_16x16x32_bf16 v[78:81], v[180:183], v[204:207], v[78:81]
	v_mfma_f32_16x16x32_bf16 v[70:73], v[170:173], v[212:215], v[70:73]
	v_mfma_f32_16x16x32_bf16 v[66:69], v[180:183], v[212:215], v[66:69]
	s_barrier
	s_setprio 0
	s_add_i32 s81, s69, s61
	s_add_u32 s98, s56, 0x80
	s_addc_u32 s99, s57, 0
	s_mov_b32 m0, s81
	ds_read_b128 v[184:187], v141 offset:16384
	ds_read_b128 v[188:191], v141 offset:17408
	ds_read_b128 v[192:195], v141 offset:18432
	ds_read_b128 v[196:199], v141 offset:19456
	ds_read_b128 v[200:203], v141 offset:20480
	ds_read_b128 v[204:207], v141 offset:21504
	ds_read_b128 v[208:211], v141 offset:22528
	ds_read_b128 v[212:215], v141 offset:23552
	global_load_lds_dwordx4 v152, s[56:57]
	s_add_i32 m0, s81, 0x2000
	s_add_u32 s82, s56, 0x80000
	s_addc_u32 s83, s57, 0
	s_add_i32 s81, s70, s61
	global_load_lds_dwordx4 v156, s[56:57]
	s_mov_b32 m0, s81
	s_nop 0
	global_load_lds_dwordx4 v152, s[82:83]
	s_add_i32 m0, s81, 0x2000
	s_nop 0
	global_load_lds_dwordx4 v156, s[82:83]
	s_add_u32 s100, s58, 0x80
	s_addc_u32 s101, s59, 0
	s_mov_b32 m0, s53
	s_nop 0
	global_load_lds_dwordx4 v150, s[58:59]
	s_mov_b32 m0, s62
	s_nop 0
	global_load_lds_dwordx4 v154, s[58:59]
	s_waitcnt vmcnt(8)
	s_waitcnt lgkmcnt(0)
	s_setprio 1
	s_barrier
	v_mfma_f32_16x16x32_bf16 v[62:65], v[142:145], v[184:187], 0
	v_mfma_f32_16x16x32_bf16 v[58:61], v[158:161], v[184:187], 0
	v_mfma_f32_16x16x32_bf16 v[50:53], v[142:145], v[192:195], 0
	v_mfma_f32_16x16x32_bf16 v[42:45], v[158:161], v[192:195], 0
	v_mfma_f32_16x16x32_bf16 v[34:37], v[142:145], v[200:203], 0
	v_mfma_f32_16x16x32_bf16 v[26:29], v[158:161], v[200:203], 0
	v_mfma_f32_16x16x32_bf16 v[18:21], v[142:145], v[208:211], 0
	v_mfma_f32_16x16x32_bf16 v[10:13], v[158:161], v[208:211], 0
	v_mfma_f32_16x16x32_bf16 v[62:65], v[146:149], v[188:191], v[62:65]
	v_mfma_f32_16x16x32_bf16 v[58:61], v[162:165], v[188:191], v[58:61]
	v_mfma_f32_16x16x32_bf16 v[50:53], v[146:149], v[196:199], v[50:53]
	v_mfma_f32_16x16x32_bf16 v[42:45], v[162:165], v[196:199], v[42:45]
	v_mfma_f32_16x16x32_bf16 v[34:37], v[146:149], v[204:207], v[34:37]
	v_mfma_f32_16x16x32_bf16 v[26:29], v[162:165], v[204:207], v[26:29]
	v_mfma_f32_16x16x32_bf16 v[18:21], v[146:149], v[212:215], v[18:21]
	v_mfma_f32_16x16x32_bf16 v[10:13], v[162:165], v[212:215], v[10:13]
	s_setprio 0
	s_setprio 1
	v_mfma_f32_16x16x32_bf16 v[54:57], v[166:169], v[184:187], 0
	v_mfma_f32_16x16x32_bf16 v[46:49], v[174:177], v[184:187], 0
	v_mfma_f32_16x16x32_bf16 v[38:41], v[166:169], v[192:195], 0
	v_mfma_f32_16x16x32_bf16 v[30:33], v[174:177], v[192:195], 0
	v_mfma_f32_16x16x32_bf16 v[22:25], v[166:169], v[200:203], 0
	v_mfma_f32_16x16x32_bf16 v[14:17], v[174:177], v[200:203], 0
	v_mfma_f32_16x16x32_bf16 v[6:9], v[166:169], v[208:211], 0
	v_mfma_f32_16x16x32_bf16 v[2:5], v[174:177], v[208:211], 0
	v_mfma_f32_16x16x32_bf16 v[54:57], v[170:173], v[188:191], v[54:57]
	v_mfma_f32_16x16x32_bf16 v[46:49], v[180:183], v[188:191], v[46:49]
	v_mfma_f32_16x16x32_bf16 v[38:41], v[170:173], v[196:199], v[38:41]
	v_mfma_f32_16x16x32_bf16 v[30:33], v[180:183], v[196:199], v[30:33]
	v_mfma_f32_16x16x32_bf16 v[22:25], v[170:173], v[204:207], v[22:25]
	v_mfma_f32_16x16x32_bf16 v[14:17], v[180:183], v[204:207], v[14:17]
	v_mfma_f32_16x16x32_bf16 v[6:9], v[170:173], v[212:215], v[6:9]
	v_mfma_f32_16x16x32_bf16 v[2:5], v[180:183], v[212:215], v[2:5]
	s_barrier
	s_setprio 0
	s_add_i32 s81, 0, 0x18000
	s_add_i32 s82, 0, 0x1c000
	ds_read_b128 v[142:145], v139 offset:32768
	ds_read_b128 v[146:149], v139 offset:33792
	ds_read_b128 v[158:161], v139 offset:34816
	ds_read_b128 v[162:165], v139 offset:35840
	ds_read_b128 v[166:169], v140 offset:32768
	ds_read_b128 v[170:173], v140 offset:33792
	ds_read_b128 v[174:177], v140 offset:34816
	ds_read_b128 v[180:183], v140 offset:35840
	s_add_u32 s58, s58, 0x80000
	s_addc_u32 s59, s59, 0
	s_mov_b32 m0, s63
	ds_read_b128 v[184:187], v141 offset:32768
	ds_read_b128 v[188:191], v141 offset:33792
	ds_read_b128 v[192:195], v141 offset:34816
	ds_read_b128 v[196:199], v141 offset:35840
	ds_read_b128 v[200:203], v141 offset:36864
	ds_read_b128 v[204:207], v141 offset:37888
	ds_read_b128 v[208:211], v141 offset:38912
	ds_read_b128 v[212:215], v141 offset:39936
	global_load_lds_dwordx4 v150, s[58:59]
	s_mov_b32 m0, s64
	s_nop 0
	global_load_lds_dwordx4 v154, s[58:59]
	s_waitcnt vmcnt(8)
	s_waitcnt lgkmcnt(0)
	s_setprio 1
	s_barrier
	v_mfma_f32_16x16x32_bf16 v[126:129], v[142:145], v[184:187], v[126:129]
	v_mfma_f32_16x16x32_bf16 v[122:125], v[158:161], v[184:187], v[122:125]
	v_mfma_f32_16x16x32_bf16 v[114:117], v[142:145], v[192:195], v[114:117]
	v_mfma_f32_16x16x32_bf16 v[106:109], v[158:161], v[192:195], v[106:109]
	v_mfma_f32_16x16x32_bf16 v[98:101], v[142:145], v[200:203], v[98:101]
	v_mfma_f32_16x16x32_bf16 v[90:93], v[158:161], v[200:203], v[90:93]
	v_mfma_f32_16x16x32_bf16 v[82:85], v[142:145], v[208:211], v[82:85]
	v_mfma_f32_16x16x32_bf16 v[74:77], v[158:161], v[208:211], v[74:77]
	v_mfma_f32_16x16x32_bf16 v[126:129], v[146:149], v[188:191], v[126:129]
	v_mfma_f32_16x16x32_bf16 v[122:125], v[162:165], v[188:191], v[122:125]
	v_mfma_f32_16x16x32_bf16 v[114:117], v[146:149], v[196:199], v[114:117]
	v_mfma_f32_16x16x32_bf16 v[106:109], v[162:165], v[196:199], v[106:109]
	v_mfma_f32_16x16x32_bf16 v[98:101], v[146:149], v[204:207], v[98:101]
	v_mfma_f32_16x16x32_bf16 v[90:93], v[162:165], v[204:207], v[90:93]
	v_mfma_f32_16x16x32_bf16 v[82:85], v[146:149], v[212:215], v[82:85]
	v_mfma_f32_16x16x32_bf16 v[74:77], v[162:165], v[212:215], v[74:77]
	s_setprio 0
	s_setprio 1
	v_mfma_f32_16x16x32_bf16 v[118:121], v[166:169], v[184:187], v[118:121]
	v_mfma_f32_16x16x32_bf16 v[110:113], v[174:177], v[184:187], v[110:113]
	v_mfma_f32_16x16x32_bf16 v[102:105], v[166:169], v[192:195], v[102:105]
	v_mfma_f32_16x16x32_bf16 v[94:97], v[174:177], v[192:195], v[94:97]
	v_mfma_f32_16x16x32_bf16 v[86:89], v[166:169], v[200:203], v[86:89]
	v_mfma_f32_16x16x32_bf16 v[78:81], v[174:177], v[200:203], v[78:81]
	v_mfma_f32_16x16x32_bf16 v[70:73], v[166:169], v[208:211], v[70:73]
	v_mfma_f32_16x16x32_bf16 v[66:69], v[174:177], v[208:211], v[66:69]
	v_mfma_f32_16x16x32_bf16 v[118:121], v[170:173], v[188:191], v[118:121]
	v_mfma_f32_16x16x32_bf16 v[110:113], v[180:183], v[188:191], v[110:113]
	v_mfma_f32_16x16x32_bf16 v[102:105], v[170:173], v[196:199], v[102:105]
	v_mfma_f32_16x16x32_bf16 v[94:97], v[180:183], v[196:199], v[94:97]
	v_mfma_f32_16x16x32_bf16 v[86:89], v[170:173], v[204:207], v[86:89]
	v_mfma_f32_16x16x32_bf16 v[78:81], v[180:183], v[204:207], v[78:81]
	v_mfma_f32_16x16x32_bf16 v[70:73], v[170:173], v[212:215], v[70:73]
	v_mfma_f32_16x16x32_bf16 v[66:69], v[180:183], v[212:215], v[66:69]
	s_barrier
	s_setprio 0
	s_add_i32 s58, s81, s61
	s_mov_b32 m0, s58
	ds_read_b128 v[184:187], v141 offset:49152
	ds_read_b128 v[188:191], v141 offset:50176
	ds_read_b128 v[192:195], v141 offset:51200
	ds_read_b128 v[196:199], v141 offset:52224
	ds_read_b128 v[200:203], v141 offset:53248
	ds_read_b128 v[204:207], v141 offset:54272
	ds_read_b128 v[208:211], v141 offset:55296
	ds_read_b128 v[212:215], v141 offset:56320
	global_load_lds_dwordx4 v152, s[98:99]
	s_add_i32 m0, s58, 0x2000
	s_add_u32 s56, s56, 0x80080
	s_addc_u32 s57, s57, 0
	s_add_i32 s58, s82, s61
	global_load_lds_dwordx4 v156, s[98:99]
	s_mov_b32 m0, s58
	s_nop 0
	global_load_lds_dwordx4 v152, s[56:57]
	s_add_i32 m0, s58, 0x2000
	s_nop 0
	global_load_lds_dwordx4 v156, s[56:57]
	s_mov_b32 m0, s66
	s_nop 0
	global_load_lds_dwordx4 v150, s[100:101]
	s_mov_b32 m0, s67
	s_nop 0
	global_load_lds_dwordx4 v154, s[100:101]
	s_waitcnt vmcnt(8)
	s_waitcnt lgkmcnt(0)
	s_setprio 1
	s_barrier
	v_mfma_f32_16x16x32_bf16 v[62:65], v[142:145], v[184:187], v[62:65]
	v_mfma_f32_16x16x32_bf16 v[58:61], v[158:161], v[184:187], v[58:61]
	v_mfma_f32_16x16x32_bf16 v[50:53], v[142:145], v[192:195], v[50:53]
	v_mfma_f32_16x16x32_bf16 v[42:45], v[158:161], v[192:195], v[42:45]
	v_mfma_f32_16x16x32_bf16 v[34:37], v[142:145], v[200:203], v[34:37]
	v_mfma_f32_16x16x32_bf16 v[26:29], v[158:161], v[200:203], v[26:29]
	v_mfma_f32_16x16x32_bf16 v[18:21], v[142:145], v[208:211], v[18:21]
	v_mfma_f32_16x16x32_bf16 v[10:13], v[158:161], v[208:211], v[10:13]
	v_mfma_f32_16x16x32_bf16 v[62:65], v[146:149], v[188:191], v[62:65]
	v_mfma_f32_16x16x32_bf16 v[58:61], v[162:165], v[188:191], v[58:61]
	v_mfma_f32_16x16x32_bf16 v[50:53], v[146:149], v[196:199], v[50:53]
	v_mfma_f32_16x16x32_bf16 v[42:45], v[162:165], v[196:199], v[42:45]
	v_mfma_f32_16x16x32_bf16 v[34:37], v[146:149], v[204:207], v[34:37]
	v_mfma_f32_16x16x32_bf16 v[26:29], v[162:165], v[204:207], v[26:29]
	v_mfma_f32_16x16x32_bf16 v[18:21], v[146:149], v[212:215], v[18:21]
	v_mfma_f32_16x16x32_bf16 v[10:13], v[162:165], v[212:215], v[10:13]
	s_setprio 0
	s_setprio 1
	v_mfma_f32_16x16x32_bf16 v[54:57], v[166:169], v[184:187], v[54:57]
	v_mfma_f32_16x16x32_bf16 v[46:49], v[174:177], v[184:187], v[46:49]
	v_mfma_f32_16x16x32_bf16 v[38:41], v[166:169], v[192:195], v[38:41]
	v_mfma_f32_16x16x32_bf16 v[30:33], v[174:177], v[192:195], v[30:33]
	v_mfma_f32_16x16x32_bf16 v[22:25], v[166:169], v[200:203], v[22:25]
	v_mfma_f32_16x16x32_bf16 v[14:17], v[174:177], v[200:203], v[14:17]
	v_mfma_f32_16x16x32_bf16 v[6:9], v[166:169], v[208:211], v[6:9]
	v_mfma_f32_16x16x32_bf16 v[2:5], v[174:177], v[208:211], v[2:5]
	v_mfma_f32_16x16x32_bf16 v[54:57], v[170:173], v[188:191], v[54:57]
	v_mfma_f32_16x16x32_bf16 v[46:49], v[180:183], v[188:191], v[46:49]
	v_mfma_f32_16x16x32_bf16 v[38:41], v[170:173], v[196:199], v[38:41]
	v_mfma_f32_16x16x32_bf16 v[30:33], v[180:183], v[196:199], v[30:33]
	v_mfma_f32_16x16x32_bf16 v[22:25], v[170:173], v[204:207], v[22:25]
	v_mfma_f32_16x16x32_bf16 v[14:17], v[180:183], v[204:207], v[14:17]
	v_mfma_f32_16x16x32_bf16 v[6:9], v[170:173], v[212:215], v[6:9]
	v_mfma_f32_16x16x32_bf16 v[2:5], v[180:183], v[212:215], v[2:5]
	s_barrier
	s_setprio 0
	s_add_i32 s80, s80, 2
	s_add_u32 s54, s54, 0x100
	s_addc_u32 s55, s55, 0
	s_add_u32 s78, s78, 0x100
	s_addc_u32 s79, s79, 0
	s_cmp_gt_u32 s80, 29

.LBB0_1401:
	ds_read_b128 v[130:133], v183
	ds_read_b128 v[134:137], v183 offset:1024
	ds_read_b128 v[138:141], v183 offset:2048
	ds_read_b128 v[142:145], v183 offset:3072
	ds_read_b128 v[162:165], v184
	ds_read_b128 v[166:169], v184 offset:1024
	ds_read_b128 v[170:173], v184 offset:2048
	ds_read_b128 v[174:177], v184 offset:3072
	ds_read_b128 v[188:191], v185
	ds_read_b128 v[192:195], v185 offset:1024
	ds_read_b128 v[196:199], v185 offset:2048
	ds_read_b128 v[200:203], v185 offset:3072
	ds_read_b128 v[204:207], v185 offset:4096
	ds_read_b128 v[208:211], v185 offset:5120
	ds_read_b128 v[212:215], v185 offset:6144
	ds_read_b128 v[216:219], v185 offset:7168
	s_add_i32 s58, s58, 1
	s_mul_i32 s10, s58, s62
	s_mul_hi_u32 s11, s58, s33
	s_add_i32 s11, s11, s10
	s_mul_i32 s10, s58, s33
	s_add_u32 s40, s10, s18
	s_addc_u32 s41, s11, s19
	v_cmp_gt_i64_e32 vcc, s[40:41], v[160:161]
	v_cmp_lt_i64_e64 s[10:11], s[40:41], v[158:159]
	s_cbranch_vccnz .LBB0_1407
	s_ashr_i32 s36, s40, 31
	s_lshr_b32 s36, s36, 29
	s_add_i32 s38, s40, s36
	s_and_b32 s36, s38, -8
	s_sub_i32 s39, s40, s36
	s_cmp_gt_i32 s39, -1
	s_mov_b64 s[36:37], -1
	s_cbranch_scc0 .LBB0_1404
	s_lshl_b32 s40, s39, 7
	s_mov_b64 s[36:37], 0

.LBB0_1407:
	s_ashr_i32 s39, s38, 31
	s_lshl_b64 s[40:41], s[38:39], 20
	s_add_u32 s40, s22, s40
	s_addc_u32 s41, s23, s41
	s_and_b64 s[42:43], s[10:11], exec
	s_cselect_b32 s39, s41, s47
	s_cselect_b32 s66, s40, s46
	s_ashr_i32 s37, s36, 31
	s_lshl_b64 s[42:43], s[36:37], 20
	s_add_u32 s42, s28, s42
	s_addc_u32 s43, s29, s43
	s_and_b64 s[52:53], s[10:11], exec
	s_cselect_b32 s37, s43, s49
	s_cselect_b32 s67, s42, s48
	s_add_u32 s46, s46, 0x80080
	s_addc_u32 s47, s47, 0
	s_add_u32 s68, s48, 0x100
	s_addc_u32 s69, s49, 0
	s_mov_b32 s70, -2
	s_add_u32 s48, s46, 0xfff80080
	s_addc_u32 s49, s47, -1
	s_cmp_eq_u32 s70, 28
	s_cselect_b32 s53, s39, s49
	s_cselect_b32 s52, s66, s48
	s_cselect_b32 s49, s37, s69
	s_cselect_b32 s48, s67, s68
	s_add_i32 m0, s45, 0xc000
	s_nop 0
	global_load_lds_dwordx4 v154, s[46:47]
	s_add_i32 m0, s45, 0xe000
	s_nop 0
	global_load_lds_dwordx4 v156, s[46:47]
	s_waitcnt vmcnt(8)
	s_waitcnt lgkmcnt(0)
	s_setprio 1
	s_barrier
	v_mfma_f32_16x16x32_bf16 v[126:129], v[130:133], v[188:191], 0
	v_mfma_f32_16x16x32_bf16 v[122:125], v[138:141], v[188:191], 0
	v_mfma_f32_16x16x32_bf16 v[110:113], v[130:133], v[196:199], 0
	v_mfma_f32_16x16x32_bf16 v[106:109], v[138:141], v[196:199], 0
	v_mfma_f32_16x16x32_bf16 v[94:97], v[130:133], v[204:207], 0
	v_mfma_f32_16x16x32_bf16 v[90:93], v[138:141], v[204:207], 0
	v_mfma_f32_16x16x32_bf16 v[78:81], v[130:133], v[212:215], 0
	v_mfma_f32_16x16x32_bf16 v[74:77], v[138:141], v[212:215], 0
	v_mfma_f32_16x16x32_bf16 v[126:129], v[134:137], v[192:195], v[126:129]
	v_mfma_f32_16x16x32_bf16 v[122:125], v[142:145], v[192:195], v[122:125]
	v_mfma_f32_16x16x32_bf16 v[110:113], v[134:137], v[200:203], v[110:113]
	v_mfma_f32_16x16x32_bf16 v[106:109], v[142:145], v[200:203], v[106:109]
	v_mfma_f32_16x16x32_bf16 v[94:97], v[134:137], v[208:211], v[94:97]
	v_mfma_f32_16x16x32_bf16 v[90:93], v[142:145], v[208:211], v[90:93]
	v_mfma_f32_16x16x32_bf16 v[78:81], v[134:137], v[216:219], v[78:81]
	v_mfma_f32_16x16x32_bf16 v[74:77], v[142:145], v[216:219], v[74:77]
	s_setprio 0
	s_setprio 1
	v_mfma_f32_16x16x32_bf16 v[118:121], v[162:165], v[188:191], 0
	v_mfma_f32_16x16x32_bf16 v[114:117], v[170:173], v[188:191], 0
	v_mfma_f32_16x16x32_bf16 v[102:105], v[162:165], v[196:199], 0
	v_mfma_f32_16x16x32_bf16 v[98:101], v[170:173], v[196:199], 0
	v_mfma_f32_16x16x32_bf16 v[86:89], v[162:165], v[204:207], 0
	v_mfma_f32_16x16x32_bf16 v[82:85], v[170:173], v[204:207], 0
	v_mfma_f32_16x16x32_bf16 v[70:73], v[162:165], v[212:215], 0
	v_mfma_f32_16x16x32_bf16 v[66:69], v[170:173], v[212:215], 0
	v_mfma_f32_16x16x32_bf16 v[118:121], v[166:169], v[192:195], v[118:121]
	v_mfma_f32_16x16x32_bf16 v[114:117], v[174:177], v[192:195], v[114:117]
	v_mfma_f32_16x16x32_bf16 v[102:105], v[166:169], v[200:203], v[102:105]
	v_mfma_f32_16x16x32_bf16 v[98:101], v[174:177], v[200:203], v[98:101]
	v_mfma_f32_16x16x32_bf16 v[86:89], v[166:169], v[208:211], v[86:89]
	v_mfma_f32_16x16x32_bf16 v[82:85], v[174:177], v[208:211], v[82:85]
	v_mfma_f32_16x16x32_bf16 v[70:73], v[166:169], v[216:219], v[70:73]
	v_mfma_f32_16x16x32_bf16 v[66:69], v[174:177], v[216:219], v[66:69]
	s_barrier
	s_setprio 0
	s_add_i32 s71, s63, s54
	s_add_u32 s98, s48, 0x80
	s_addc_u32 s99, s49, 0
	s_mov_b32 m0, s71
	ds_read_b128 v[188:191], v185 offset:16384
	ds_read_b128 v[192:195], v185 offset:17408
	ds_read_b128 v[196:199], v185 offset:18432
	ds_read_b128 v[200:203], v185 offset:19456
	ds_read_b128 v[204:207], v185 offset:20480
	ds_read_b128 v[208:211], v185 offset:21504
	ds_read_b128 v[212:215], v185 offset:22528
	ds_read_b128 v[216:219], v185 offset:23552
	global_load_lds_dwordx4 v148, s[48:49]
	s_add_i32 m0, s71, 0x2000
	s_add_u32 s72, s48, 0x80000
	s_addc_u32 s73, s49, 0
	s_add_i32 s71, s64, s54
	global_load_lds_dwordx4 v152, s[48:49]
	s_mov_b32 m0, s71
	s_nop 0
	global_load_lds_dwordx4 v148, s[72:73]
	s_add_i32 m0, s71, 0x2000
	s_nop 0
	global_load_lds_dwordx4 v152, s[72:73]
	s_add_u32 s100, s52, 0x80
	s_addc_u32 s101, s53, 0
	s_mov_b32 m0, s45
	s_nop 0
	global_load_lds_dwordx4 v146, s[52:53]
	s_mov_b32 m0, s55
	s_nop 0
	global_load_lds_dwordx4 v150, s[52:53]
	s_waitcnt vmcnt(8)
	s_waitcnt lgkmcnt(0)
	s_setprio 1
	s_barrier
	v_mfma_f32_16x16x32_bf16 v[62:65], v[130:133], v[188:191], 0
	v_mfma_f32_16x16x32_bf16 v[58:61], v[138:141], v[188:191], 0
	v_mfma_f32_16x16x32_bf16 v[46:49], v[130:133], v[196:199], 0
	v_mfma_f32_16x16x32_bf16 v[42:45], v[138:141], v[196:199], 0
	v_mfma_f32_16x16x32_bf16 v[30:33], v[130:133], v[204:207], 0
	v_mfma_f32_16x16x32_bf16 v[26:29], v[138:141], v[204:207], 0
	v_mfma_f32_16x16x32_bf16 v[14:17], v[130:133], v[212:215], 0
	v_mfma_f32_16x16x32_bf16 v[10:13], v[138:141], v[212:215], 0
	v_mfma_f32_16x16x32_bf16 v[62:65], v[134:137], v[192:195], v[62:65]
	v_mfma_f32_16x16x32_bf16 v[58:61], v[142:145], v[192:195], v[58:61]
	v_mfma_f32_16x16x32_bf16 v[46:49], v[134:137], v[200:203], v[46:49]
	v_mfma_f32_16x16x32_bf16 v[42:45], v[142:145], v[200:203], v[42:45]
	v_mfma_f32_16x16x32_bf16 v[30:33], v[134:137], v[208:211], v[30:33]
	v_mfma_f32_16x16x32_bf16 v[26:29], v[142:145], v[208:211], v[26:29]
	v_mfma_f32_16x16x32_bf16 v[14:17], v[134:137], v[216:219], v[14:17]
	v_mfma_f32_16x16x32_bf16 v[10:13], v[142:145], v[216:219], v[10:13]
	s_setprio 0
	s_setprio 1
	v_mfma_f32_16x16x32_bf16 v[54:57], v[162:165], v[188:191], 0
	v_mfma_f32_16x16x32_bf16 v[50:53], v[170:173], v[188:191], 0
	v_mfma_f32_16x16x32_bf16 v[38:41], v[162:165], v[196:199], 0
	v_mfma_f32_16x16x32_bf16 v[34:37], v[170:173], v[196:199], 0
	v_mfma_f32_16x16x32_bf16 v[22:25], v[162:165], v[204:207], 0
	v_mfma_f32_16x16x32_bf16 v[18:21], v[170:173], v[204:207], 0
	v_mfma_f32_16x16x32_bf16 v[6:9], v[162:165], v[212:215], 0
	v_mfma_f32_16x16x32_bf16 v[2:5], v[170:173], v[212:215], 0
	v_mfma_f32_16x16x32_bf16 v[54:57], v[166:169], v[192:195], v[54:57]
	v_mfma_f32_16x16x32_bf16 v[50:53], v[174:177], v[192:195], v[50:53]
	v_mfma_f32_16x16x32_bf16 v[38:41], v[166:169], v[200:203], v[38:41]
	v_mfma_f32_16x16x32_bf16 v[34:37], v[174:177], v[200:203], v[34:37]
	v_mfma_f32_16x16x32_bf16 v[22:25], v[166:169], v[208:211], v[22:25]
	v_mfma_f32_16x16x32_bf16 v[18:21], v[174:177], v[208:211], v[18:21]
	v_mfma_f32_16x16x32_bf16 v[6:9], v[166:169], v[216:219], v[6:9]
	v_mfma_f32_16x16x32_bf16 v[2:5], v[174:177], v[216:219], v[2:5]
	s_barrier
	s_setprio 0
	s_add_i32 s71, 0, 0x18000
	s_add_i32 s72, 0, 0x1c000
	ds_read_b128 v[130:133], v183 offset:32768
	ds_read_b128 v[134:137], v183 offset:33792
	ds_read_b128 v[138:141], v183 offset:34816
	ds_read_b128 v[142:145], v183 offset:35840
	ds_read_b128 v[162:165], v184 offset:32768
	ds_read_b128 v[166:169], v184 offset:33792
	ds_read_b128 v[170:173], v184 offset:34816
	ds_read_b128 v[174:177], v184 offset:35840
	s_add_u32 s52, s52, 0x80000
	s_addc_u32 s53, s53, 0
	s_mov_b32 m0, s56
	ds_read_b128 v[188:191], v185 offset:32768
	ds_read_b128 v[192:195], v185 offset:33792
	ds_read_b128 v[196:199], v185 offset:34816
	ds_read_b128 v[200:203], v185 offset:35840
	ds_read_b128 v[204:207], v185 offset:36864
	ds_read_b128 v[208:211], v185 offset:37888
	ds_read_b128 v[212:215], v185 offset:38912
	ds_read_b128 v[216:219], v185 offset:39936
	global_load_lds_dwordx4 v146, s[52:53]
	s_mov_b32 m0, s57
	s_nop 0
	global_load_lds_dwordx4 v150, s[52:53]
	s_waitcnt vmcnt(8)
	s_waitcnt lgkmcnt(0)
	s_setprio 1
	s_barrier
	v_mfma_f32_16x16x32_bf16 v[126:129], v[130:133], v[188:191], v[126:129]
	v_mfma_f32_16x16x32_bf16 v[122:125], v[138:141], v[188:191], v[122:125]
	v_mfma_f32_16x16x32_bf16 v[110:113], v[130:133], v[196:199], v[110:113]
	v_mfma_f32_16x16x32_bf16 v[106:109], v[138:141], v[196:199], v[106:109]
	v_mfma_f32_16x16x32_bf16 v[94:97], v[130:133], v[204:207], v[94:97]
	v_mfma_f32_16x16x32_bf16 v[90:93], v[138:141], v[204:207], v[90:93]
	v_mfma_f32_16x16x32_bf16 v[78:81], v[130:133], v[212:215], v[78:81]
	v_mfma_f32_16x16x32_bf16 v[74:77], v[138:141], v[212:215], v[74:77]
	v_mfma_f32_16x16x32_bf16 v[126:129], v[134:137], v[192:195], v[126:129]
	v_mfma_f32_16x16x32_bf16 v[122:125], v[142:145], v[192:195], v[122:125]
	v_mfma_f32_16x16x32_bf16 v[110:113], v[134:137], v[200:203], v[110:113]
	v_mfma_f32_16x16x32_bf16 v[106:109], v[142:145], v[200:203], v[106:109]
	v_mfma_f32_16x16x32_bf16 v[94:97], v[134:137], v[208:211], v[94:97]
	v_mfma_f32_16x16x32_bf16 v[90:93], v[142:145], v[208:211], v[90:93]
	v_mfma_f32_16x16x32_bf16 v[78:81], v[134:137], v[216:219], v[78:81]
	v_mfma_f32_16x16x32_bf16 v[74:77], v[142:145], v[216:219], v[74:77]
	s_setprio 0
	s_setprio 1
	v_mfma_f32_16x16x32_bf16 v[118:121], v[162:165], v[188:191], v[118:121]
	v_mfma_f32_16x16x32_bf16 v[114:117], v[170:173], v[188:191], v[114:117]
	v_mfma_f32_16x16x32_bf16 v[102:105], v[162:165], v[196:199], v[102:105]
	v_mfma_f32_16x16x32_bf16 v[98:101], v[170:173], v[196:199], v[98:101]
	v_mfma_f32_16x16x32_bf16 v[86:89], v[162:165], v[204:207], v[86:89]
	v_mfma_f32_16x16x32_bf16 v[82:85], v[170:173], v[204:207], v[82:85]
	v_mfma_f32_16x16x32_bf16 v[70:73], v[162:165], v[212:215], v[70:73]
	v_mfma_f32_16x16x32_bf16 v[66:69], v[170:173], v[212:215], v[66:69]
	v_mfma_f32_16x16x32_bf16 v[118:121], v[166:169], v[192:195], v[118:121]
	v_mfma_f32_16x16x32_bf16 v[114:117], v[174:177], v[192:195], v[114:117]
	v_mfma_f32_16x16x32_bf16 v[102:105], v[166:169], v[200:203], v[102:105]
	v_mfma_f32_16x16x32_bf16 v[98:101], v[174:177], v[200:203], v[98:101]
	v_mfma_f32_16x16x32_bf16 v[86:89], v[166:169], v[208:211], v[86:89]
	v_mfma_f32_16x16x32_bf16 v[82:85], v[174:177], v[208:211], v[82:85]
	v_mfma_f32_16x16x32_bf16 v[70:73], v[166:169], v[216:219], v[70:73]
	v_mfma_f32_16x16x32_bf16 v[66:69], v[174:177], v[216:219], v[66:69]
	s_barrier
	s_setprio 0
	s_add_i32 s52, s71, s54
	s_mov_b32 m0, s52
	ds_read_b128 v[188:191], v185 offset:49152
	ds_read_b128 v[192:195], v185 offset:50176
	ds_read_b128 v[196:199], v185 offset:51200
	ds_read_b128 v[200:203], v185 offset:52224
	ds_read_b128 v[204:207], v185 offset:53248
	ds_read_b128 v[208:211], v185 offset:54272
	ds_read_b128 v[212:215], v185 offset:55296
	ds_read_b128 v[216:219], v185 offset:56320
	global_load_lds_dwordx4 v148, s[98:99]
	s_add_i32 m0, s52, 0x2000
	s_add_u32 s48, s48, 0x80080
	s_addc_u32 s49, s49, 0
	s_add_i32 s52, s72, s54
	global_load_lds_dwordx4 v152, s[98:99]
	s_mov_b32 m0, s52
	s_nop 0
	global_load_lds_dwordx4 v148, s[48:49]
	s_add_i32 m0, s52, 0x2000
	s_nop 0
	global_load_lds_dwordx4 v152, s[48:49]
	s_mov_b32 m0, s60
	s_nop 0
	global_load_lds_dwordx4 v146, s[100:101]
	s_mov_b32 m0, s61
	s_nop 0
	global_load_lds_dwordx4 v150, s[100:101]
	s_waitcnt vmcnt(8)
	s_waitcnt lgkmcnt(0)
	s_setprio 1
	s_barrier
	v_mfma_f32_16x16x32_bf16 v[62:65], v[130:133], v[188:191], v[62:65]
	v_mfma_f32_16x16x32_bf16 v[58:61], v[138:141], v[188:191], v[58:61]
	v_mfma_f32_16x16x32_bf16 v[46:49], v[130:133], v[196:199], v[46:49]
	v_mfma_f32_16x16x32_bf16 v[42:45], v[138:141], v[196:199], v[42:45]
	v_mfma_f32_16x16x32_bf16 v[30:33], v[130:133], v[204:207], v[30:33]
	v_mfma_f32_16x16x32_bf16 v[26:29], v[138:141], v[204:207], v[26:29]
	v_mfma_f32_16x16x32_bf16 v[14:17], v[130:133], v[212:215], v[14:17]
	v_mfma_f32_16x16x32_bf16 v[10:13], v[138:141], v[212:215], v[10:13]
	v_mfma_f32_16x16x32_bf16 v[62:65], v[134:137], v[192:195], v[62:65]
	v_mfma_f32_16x16x32_bf16 v[58:61], v[142:145], v[192:195], v[58:61]
	v_mfma_f32_16x16x32_bf16 v[46:49], v[134:137], v[200:203], v[46:49]
	v_mfma_f32_16x16x32_bf16 v[42:45], v[142:145], v[200:203], v[42:45]
	v_mfma_f32_16x16x32_bf16 v[30:33], v[134:137], v[208:211], v[30:33]
	v_mfma_f32_16x16x32_bf16 v[26:29], v[142:145], v[208:211], v[26:29]
	v_mfma_f32_16x16x32_bf16 v[14:17], v[134:137], v[216:219], v[14:17]
	v_mfma_f32_16x16x32_bf16 v[10:13], v[142:145], v[216:219], v[10:13]
	s_setprio 0
	s_setprio 1
	v_mfma_f32_16x16x32_bf16 v[54:57], v[162:165], v[188:191], v[54:57]
	v_mfma_f32_16x16x32_bf16 v[50:53], v[170:173], v[188:191], v[50:53]
	v_mfma_f32_16x16x32_bf16 v[38:41], v[162:165], v[196:199], v[38:41]
	v_mfma_f32_16x16x32_bf16 v[34:37], v[170:173], v[196:199], v[34:37]
	v_mfma_f32_16x16x32_bf16 v[22:25], v[162:165], v[204:207], v[22:25]
	v_mfma_f32_16x16x32_bf16 v[18:21], v[170:173], v[204:207], v[18:21]
	v_mfma_f32_16x16x32_bf16 v[6:9], v[162:165], v[212:215], v[6:9]
	v_mfma_f32_16x16x32_bf16 v[2:5], v[170:173], v[212:215], v[2:5]
	v_mfma_f32_16x16x32_bf16 v[54:57], v[166:169], v[192:195], v[54:57]
	v_mfma_f32_16x16x32_bf16 v[50:53], v[174:177], v[192:195], v[50:53]
	v_mfma_f32_16x16x32_bf16 v[38:41], v[166:169], v[200:203], v[38:41]
	v_mfma_f32_16x16x32_bf16 v[34:37], v[174:177], v[200:203], v[34:37]
	v_mfma_f32_16x16x32_bf16 v[22:25], v[166:169], v[208:211], v[22:25]
	v_mfma_f32_16x16x32_bf16 v[18:21], v[174:177], v[208:211], v[18:21]
	v_mfma_f32_16x16x32_bf16 v[6:9], v[166:169], v[216:219], v[6:9]
	v_mfma_f32_16x16x32_bf16 v[2:5], v[174:177], v[216:219], v[2:5]
	s_barrier
	s_setprio 0
	s_add_i32 s70, s70, 2
	s_add_u32 s46, s46, 0x100
	s_addc_u32 s47, s47, 0
	s_add_u32 s68, s68, 0x100
	s_addc_u32 s69, s69, 0
	s_cmp_gt_u32 s70, 29

.LBB0_1476:
	ds_read_b128 v[132:135], v174
	ds_read_b128 v[158:161], v174 offset:1024
	ds_read_b128 v[166:169], v174 offset:2048
	ds_read_b128 v[170:173], v174 offset:3072
	ds_read_b128 v[182:185], v175
	ds_read_b128 v[186:189], v175 offset:1024
	ds_read_b128 v[190:193], v175 offset:2048
	ds_read_b128 v[194:197], v175 offset:3072
	ds_read_b128 v[198:201], v176
	ds_read_b128 v[202:205], v176 offset:1024
	ds_read_b128 v[206:209], v176 offset:2048
	ds_read_b128 v[210:213], v176 offset:3072
	ds_read_b128 v[214:217], v176 offset:4096
	ds_read_b128 v[218:221], v176 offset:5120
	ds_read_b128 v[222:225], v176 offset:6144
	ds_read_b128 v[226:229], v176 offset:7168
	s_add_i32 s52, s52, 1
	s_mul_i32 s2, s52, s53
	s_mul_hi_u32 s3, s52, s33
	s_add_i32 s3, s3, s2
	s_mul_i32 s2, s52, s33
	s_add_u32 s6, s2, s18
	s_addc_u32 s7, s3, s42
	v_cmp_gt_i64_e32 vcc, s[6:7], v[152:153]
	s_mov_b32 s58, s10
	v_cmp_lt_i64_e64 s[2:3], s[6:7], v[150:151]
	s_cbranch_vccnz .LBB0_1478
	s_ashr_i32 s7, s6, 31
	s_lshr_b32 s7, s7, 29
	s_add_i32 s7, s6, s7
	s_ashr_i32 s9, s7, 3
	s_and_b32 s7, s7, -8
	s_sub_i32 s6, s6, s7
	s_cmp_lt_i32 s6, 0
	s_cselect_b32 s7, s43, 0x2c0
	s_mul_i32 s6, s6, s7
	s_add_i32 s6, s6, s9
	s_mul_hi_i32 s7, s6, 0x2e8ba2e9
	s_lshr_b32 s9, s7, 31
	s_ashr_i32 s7, s7, 6
	s_add_i32 s7, s7, s9
	s_lshl_b32 s9, s7, 3
	s_mulk_i32 s7, 0x160
	s_sub_i32 s6, s6, s7
	s_lshr_b32 s36, s6, 3
	s_and_b32 s6, s6, 7
	s_add_i32 s10, s9, s6
.LBB0_1478:
	s_ashr_i32 s11, s10, 31
	s_lshl_b64 s[6:7], s[10:11], 20
	s_add_u32 s38, s19, s6
	s_addc_u32 s39, s22, s7
	s_and_b64 s[6:7], s[2:3], exec
	s_cselect_b32 s9, s39, s1
	s_cselect_b32 s11, s38, s0
	s_ashr_i32 s37, s36, 31
	s_lshl_b64 s[6:7], s[36:37], 20
	s_add_u32 s40, s23, s6
	s_addc_u32 s41, s28, s7
	s_and_b64 s[6:7], s[2:3], exec
	s_cselect_b32 s37, s41, s5
	s_cselect_b32 s60, s40, s4
	s_add_u32 s0, s0, 0x80080
	s_addc_u32 s1, s1, 0
	s_add_u32 s61, s4, 0x100
	s_addc_u32 s62, s5, 0
	s_mov_b32 s63, -2
	s_add_u32 s4, s0, 0xfff80080
	s_addc_u32 s5, s1, -1
	s_cmp_eq_u32 s63, 28
	s_cselect_b32 s7, s9, s5
	s_cselect_b32 s6, s11, s4
	s_cselect_b32 s5, s37, s62
	s_cselect_b32 s4, s60, s61
	s_add_i32 m0, s44, 0xc000
	s_nop 0
	global_load_lds_dwordx4 v146, s[0:1]
	s_add_i32 m0, s44, 0xe000
	s_nop 0
	global_load_lds_dwordx4 v148, s[0:1]
	s_waitcnt vmcnt(8)
	s_waitcnt lgkmcnt(0)
	s_setprio 1
	s_barrier
	v_mfma_f32_16x16x32_bf16 v[128:131], v[132:135], v[198:201], 0
	v_mfma_f32_16x16x32_bf16 v[124:127], v[166:169], v[198:201], 0
	v_mfma_f32_16x16x32_bf16 v[112:115], v[132:135], v[206:209], 0
	v_mfma_f32_16x16x32_bf16 v[108:111], v[166:169], v[206:209], 0
	v_mfma_f32_16x16x32_bf16 v[96:99], v[132:135], v[214:217], 0
	v_mfma_f32_16x16x32_bf16 v[92:95], v[166:169], v[214:217], 0
	v_mfma_f32_16x16x32_bf16 v[80:83], v[132:135], v[222:225], 0
	v_mfma_f32_16x16x32_bf16 v[76:79], v[166:169], v[222:225], 0
	v_mfma_f32_16x16x32_bf16 v[128:131], v[158:161], v[202:205], v[128:131]
	v_mfma_f32_16x16x32_bf16 v[124:127], v[170:173], v[202:205], v[124:127]
	v_mfma_f32_16x16x32_bf16 v[112:115], v[158:161], v[210:213], v[112:115]
	v_mfma_f32_16x16x32_bf16 v[108:111], v[170:173], v[210:213], v[108:111]
	v_mfma_f32_16x16x32_bf16 v[96:99], v[158:161], v[218:221], v[96:99]
	v_mfma_f32_16x16x32_bf16 v[92:95], v[170:173], v[218:221], v[92:95]
	v_mfma_f32_16x16x32_bf16 v[80:83], v[158:161], v[226:229], v[80:83]
	v_mfma_f32_16x16x32_bf16 v[76:79], v[170:173], v[226:229], v[76:79]
	s_setprio 0
	s_setprio 1
	v_mfma_f32_16x16x32_bf16 v[120:123], v[182:185], v[198:201], 0
	v_mfma_f32_16x16x32_bf16 v[116:119], v[190:193], v[198:201], 0
	v_mfma_f32_16x16x32_bf16 v[104:107], v[182:185], v[206:209], 0
	v_mfma_f32_16x16x32_bf16 v[100:103], v[190:193], v[206:209], 0
	v_mfma_f32_16x16x32_bf16 v[88:91], v[182:185], v[214:217], 0
	v_mfma_f32_16x16x32_bf16 v[84:87], v[190:193], v[214:217], 0
	v_mfma_f32_16x16x32_bf16 v[72:75], v[182:185], v[222:225], 0
	v_mfma_f32_16x16x32_bf16 v[68:71], v[190:193], v[222:225], 0
	v_mfma_f32_16x16x32_bf16 v[120:123], v[186:189], v[202:205], v[120:123]
	v_mfma_f32_16x16x32_bf16 v[116:119], v[194:197], v[202:205], v[116:119]
	v_mfma_f32_16x16x32_bf16 v[104:107], v[186:189], v[210:213], v[104:107]
	v_mfma_f32_16x16x32_bf16 v[100:103], v[194:197], v[210:213], v[100:103]
	v_mfma_f32_16x16x32_bf16 v[88:91], v[186:189], v[218:221], v[88:91]
	v_mfma_f32_16x16x32_bf16 v[84:87], v[194:197], v[218:221], v[84:87]
	v_mfma_f32_16x16x32_bf16 v[72:75], v[186:189], v[226:229], v[72:75]
	v_mfma_f32_16x16x32_bf16 v[68:71], v[194:197], v[226:229], v[68:71]
	s_barrier
	s_setprio 0
	s_add_i32 s64, s54, s29
	s_add_u32 s98, s4, 0x80
	s_addc_u32 s99, s5, 0
	s_mov_b32 m0, s64
	ds_read_b128 v[198:201], v176 offset:16384
	ds_read_b128 v[202:205], v176 offset:17408
	ds_read_b128 v[206:209], v176 offset:18432
	ds_read_b128 v[210:213], v176 offset:19456
	ds_read_b128 v[214:217], v176 offset:20480
	ds_read_b128 v[218:221], v176 offset:21504
	ds_read_b128 v[222:225], v176 offset:22528
	ds_read_b128 v[226:229], v176 offset:23552
	global_load_lds_dwordx4 v142, s[4:5]
	s_add_i32 m0, s64, 0x2000
	s_add_u32 s64, s4, 0x80000
	s_addc_u32 s65, s5, 0
	s_add_i32 s66, s55, s29
	global_load_lds_dwordx4 v138, s[4:5]
	s_mov_b32 m0, s66
	s_nop 0
	global_load_lds_dwordx4 v142, s[64:65]
	s_add_i32 m0, s66, 0x2000
	s_nop 0
	global_load_lds_dwordx4 v138, s[64:65]
	s_add_u32 s100, s6, 0x80
	s_addc_u32 s101, s7, 0
	s_mov_b32 m0, s44
	s_nop 0
	global_load_lds_dwordx4 v144, s[6:7]
	s_mov_b32 m0, s45
	s_nop 0
	global_load_lds_dwordx4 v140, s[6:7]
	s_waitcnt vmcnt(8)
	s_waitcnt lgkmcnt(0)
	s_setprio 1
	s_barrier
	v_mfma_f32_16x16x32_bf16 v[62:65], v[132:135], v[198:201], 0
	v_mfma_f32_16x16x32_bf16 v[58:61], v[166:169], v[198:201], 0
	v_mfma_f32_16x16x32_bf16 v[46:49], v[132:135], v[206:209], 0
	v_mfma_f32_16x16x32_bf16 v[42:45], v[166:169], v[206:209], 0
	v_mfma_f32_16x16x32_bf16 v[30:33], v[132:135], v[214:217], 0
	v_mfma_f32_16x16x32_bf16 v[26:29], v[166:169], v[214:217], 0
	v_mfma_f32_16x16x32_bf16 v[14:17], v[132:135], v[222:225], 0
	v_mfma_f32_16x16x32_bf16 v[10:13], v[166:169], v[222:225], 0
	v_mfma_f32_16x16x32_bf16 v[62:65], v[158:161], v[202:205], v[62:65]
	v_mfma_f32_16x16x32_bf16 v[58:61], v[170:173], v[202:205], v[58:61]
	v_mfma_f32_16x16x32_bf16 v[46:49], v[158:161], v[210:213], v[46:49]
	v_mfma_f32_16x16x32_bf16 v[42:45], v[170:173], v[210:213], v[42:45]
	v_mfma_f32_16x16x32_bf16 v[30:33], v[158:161], v[218:221], v[30:33]
	v_mfma_f32_16x16x32_bf16 v[26:29], v[170:173], v[218:221], v[26:29]
	v_mfma_f32_16x16x32_bf16 v[14:17], v[158:161], v[226:229], v[14:17]
	v_mfma_f32_16x16x32_bf16 v[10:13], v[170:173], v[226:229], v[10:13]
	s_setprio 0
	s_setprio 1
	v_mfma_f32_16x16x32_bf16 v[54:57], v[182:185], v[198:201], 0
	v_mfma_f32_16x16x32_bf16 v[50:53], v[190:193], v[198:201], 0
	v_mfma_f32_16x16x32_bf16 v[38:41], v[182:185], v[206:209], 0
	v_mfma_f32_16x16x32_bf16 v[34:37], v[190:193], v[206:209], 0
	v_mfma_f32_16x16x32_bf16 v[22:25], v[182:185], v[214:217], 0
	v_mfma_f32_16x16x32_bf16 v[18:21], v[190:193], v[214:217], 0
	v_mfma_f32_16x16x32_bf16 v[6:9], v[182:185], v[222:225], 0
	v_mfma_f32_16x16x32_bf16 v[2:5], v[190:193], v[222:225], 0
	v_mfma_f32_16x16x32_bf16 v[54:57], v[186:189], v[202:205], v[54:57]
	v_mfma_f32_16x16x32_bf16 v[50:53], v[194:197], v[202:205], v[50:53]
	v_mfma_f32_16x16x32_bf16 v[38:41], v[186:189], v[210:213], v[38:41]
	v_mfma_f32_16x16x32_bf16 v[34:37], v[194:197], v[210:213], v[34:37]
	v_mfma_f32_16x16x32_bf16 v[22:25], v[186:189], v[218:221], v[22:25]
	v_mfma_f32_16x16x32_bf16 v[18:21], v[194:197], v[218:221], v[18:21]
	v_mfma_f32_16x16x32_bf16 v[6:9], v[186:189], v[226:229], v[6:9]
	v_mfma_f32_16x16x32_bf16 v[2:5], v[194:197], v[226:229], v[2:5]
	s_barrier
	s_setprio 0
	s_add_i32 s64, 0, 0x18000
	s_add_i32 s65, 0, 0x1c000
	ds_read_b128 v[132:135], v174 offset:32768
	ds_read_b128 v[158:161], v174 offset:33792
	ds_read_b128 v[166:169], v174 offset:34816
	ds_read_b128 v[170:173], v174 offset:35840
	ds_read_b128 v[182:185], v175 offset:32768
	ds_read_b128 v[186:189], v175 offset:33792
	ds_read_b128 v[190:193], v175 offset:34816
	ds_read_b128 v[194:197], v175 offset:35840
	s_add_u32 s6, s6, 0x80000
	s_addc_u32 s7, s7, 0
	s_mov_b32 m0, s46
	ds_read_b128 v[198:201], v176 offset:32768
	ds_read_b128 v[202:205], v176 offset:33792
	ds_read_b128 v[206:209], v176 offset:34816
	ds_read_b128 v[210:213], v176 offset:35840
	ds_read_b128 v[214:217], v176 offset:36864
	ds_read_b128 v[218:221], v176 offset:37888
	ds_read_b128 v[222:225], v176 offset:38912
	ds_read_b128 v[226:229], v176 offset:39936
	global_load_lds_dwordx4 v144, s[6:7]
	s_mov_b32 m0, s47
	s_nop 0
	global_load_lds_dwordx4 v140, s[6:7]
	s_waitcnt vmcnt(8)
	s_waitcnt lgkmcnt(0)
	s_setprio 1
	s_barrier
	v_mfma_f32_16x16x32_bf16 v[128:131], v[132:135], v[198:201], v[128:131]
	v_mfma_f32_16x16x32_bf16 v[124:127], v[166:169], v[198:201], v[124:127]
	v_mfma_f32_16x16x32_bf16 v[112:115], v[132:135], v[206:209], v[112:115]
	v_mfma_f32_16x16x32_bf16 v[108:111], v[166:169], v[206:209], v[108:111]
	v_mfma_f32_16x16x32_bf16 v[96:99], v[132:135], v[214:217], v[96:99]
	v_mfma_f32_16x16x32_bf16 v[92:95], v[166:169], v[214:217], v[92:95]
	v_mfma_f32_16x16x32_bf16 v[80:83], v[132:135], v[222:225], v[80:83]
	v_mfma_f32_16x16x32_bf16 v[76:79], v[166:169], v[222:225], v[76:79]
	v_mfma_f32_16x16x32_bf16 v[128:131], v[158:161], v[202:205], v[128:131]
	v_mfma_f32_16x16x32_bf16 v[124:127], v[170:173], v[202:205], v[124:127]
	v_mfma_f32_16x16x32_bf16 v[112:115], v[158:161], v[210:213], v[112:115]
	v_mfma_f32_16x16x32_bf16 v[108:111], v[170:173], v[210:213], v[108:111]
	v_mfma_f32_16x16x32_bf16 v[96:99], v[158:161], v[218:221], v[96:99]
	v_mfma_f32_16x16x32_bf16 v[92:95], v[170:173], v[218:221], v[92:95]
	v_mfma_f32_16x16x32_bf16 v[80:83], v[158:161], v[226:229], v[80:83]
	v_mfma_f32_16x16x32_bf16 v[76:79], v[170:173], v[226:229], v[76:79]
	s_setprio 0
	s_setprio 1
	v_mfma_f32_16x16x32_bf16 v[120:123], v[182:185], v[198:201], v[120:123]
	v_mfma_f32_16x16x32_bf16 v[116:119], v[190:193], v[198:201], v[116:119]
	v_mfma_f32_16x16x32_bf16 v[104:107], v[182:185], v[206:209], v[104:107]
	v_mfma_f32_16x16x32_bf16 v[100:103], v[190:193], v[206:209], v[100:103]
	v_mfma_f32_16x16x32_bf16 v[88:91], v[182:185], v[214:217], v[88:91]
	v_mfma_f32_16x16x32_bf16 v[84:87], v[190:193], v[214:217], v[84:87]
	v_mfma_f32_16x16x32_bf16 v[72:75], v[182:185], v[222:225], v[72:75]
	v_mfma_f32_16x16x32_bf16 v[68:71], v[190:193], v[222:225], v[68:71]
	v_mfma_f32_16x16x32_bf16 v[120:123], v[186:189], v[202:205], v[120:123]
	v_mfma_f32_16x16x32_bf16 v[116:119], v[194:197], v[202:205], v[116:119]
	v_mfma_f32_16x16x32_bf16 v[104:107], v[186:189], v[210:213], v[104:107]
	v_mfma_f32_16x16x32_bf16 v[100:103], v[194:197], v[210:213], v[100:103]
	v_mfma_f32_16x16x32_bf16 v[88:91], v[186:189], v[218:221], v[88:91]
	v_mfma_f32_16x16x32_bf16 v[84:87], v[194:197], v[218:221], v[84:87]
	v_mfma_f32_16x16x32_bf16 v[72:75], v[186:189], v[226:229], v[72:75]
	v_mfma_f32_16x16x32_bf16 v[68:71], v[194:197], v[226:229], v[68:71]
	s_barrier
	s_setprio 0
	s_add_i32 s6, s64, s29
	s_mov_b32 m0, s6
	ds_read_b128 v[198:201], v176 offset:49152
	ds_read_b128 v[202:205], v176 offset:50176
	ds_read_b128 v[206:209], v176 offset:51200
	ds_read_b128 v[210:213], v176 offset:52224
	ds_read_b128 v[214:217], v176 offset:53248
	ds_read_b128 v[218:221], v176 offset:54272
	ds_read_b128 v[222:225], v176 offset:55296
	ds_read_b128 v[226:229], v176 offset:56320
	global_load_lds_dwordx4 v142, s[98:99]
	s_add_i32 m0, s6, 0x2000
	s_add_u32 s4, s4, 0x80080
	s_addc_u32 s5, s5, 0
	s_add_i32 s6, s65, s29
	global_load_lds_dwordx4 v138, s[98:99]
	s_mov_b32 m0, s6
	s_nop 0
	global_load_lds_dwordx4 v142, s[4:5]
	s_add_i32 m0, s6, 0x2000
	s_nop 0
	global_load_lds_dwordx4 v138, s[4:5]
	s_mov_b32 m0, s48
	s_nop 0
	global_load_lds_dwordx4 v144, s[100:101]
	s_mov_b32 m0, s49
	s_nop 0
	global_load_lds_dwordx4 v140, s[100:101]
	s_waitcnt vmcnt(8)
	s_waitcnt lgkmcnt(0)
	s_setprio 1
	s_barrier
	v_mfma_f32_16x16x32_bf16 v[62:65], v[132:135], v[198:201], v[62:65]
	v_mfma_f32_16x16x32_bf16 v[58:61], v[166:169], v[198:201], v[58:61]
	v_mfma_f32_16x16x32_bf16 v[46:49], v[132:135], v[206:209], v[46:49]
	v_mfma_f32_16x16x32_bf16 v[42:45], v[166:169], v[206:209], v[42:45]
	v_mfma_f32_16x16x32_bf16 v[30:33], v[132:135], v[214:217], v[30:33]
	v_mfma_f32_16x16x32_bf16 v[26:29], v[166:169], v[214:217], v[26:29]
	v_mfma_f32_16x16x32_bf16 v[14:17], v[132:135], v[222:225], v[14:17]
	v_mfma_f32_16x16x32_bf16 v[10:13], v[166:169], v[222:225], v[10:13]
	v_mfma_f32_16x16x32_bf16 v[62:65], v[158:161], v[202:205], v[62:65]
	v_mfma_f32_16x16x32_bf16 v[58:61], v[170:173], v[202:205], v[58:61]
	v_mfma_f32_16x16x32_bf16 v[46:49], v[158:161], v[210:213], v[46:49]
	v_mfma_f32_16x16x32_bf16 v[42:45], v[170:173], v[210:213], v[42:45]
	v_mfma_f32_16x16x32_bf16 v[30:33], v[158:161], v[218:221], v[30:33]
	v_mfma_f32_16x16x32_bf16 v[26:29], v[170:173], v[218:221], v[26:29]
	v_mfma_f32_16x16x32_bf16 v[14:17], v[158:161], v[226:229], v[14:17]
	v_mfma_f32_16x16x32_bf16 v[10:13], v[170:173], v[226:229], v[10:13]
	s_setprio 0
	s_setprio 1
	v_mfma_f32_16x16x32_bf16 v[54:57], v[182:185], v[198:201], v[54:57]
	v_mfma_f32_16x16x32_bf16 v[50:53], v[190:193], v[198:201], v[50:53]
	v_mfma_f32_16x16x32_bf16 v[38:41], v[182:185], v[206:209], v[38:41]
	v_mfma_f32_16x16x32_bf16 v[34:37], v[190:193], v[206:209], v[34:37]
	v_mfma_f32_16x16x32_bf16 v[22:25], v[182:185], v[214:217], v[22:25]
	v_mfma_f32_16x16x32_bf16 v[18:21], v[190:193], v[214:217], v[18:21]
	v_mfma_f32_16x16x32_bf16 v[6:9], v[182:185], v[222:225], v[6:9]
	v_mfma_f32_16x16x32_bf16 v[2:5], v[190:193], v[222:225], v[2:5]
	v_mfma_f32_16x16x32_bf16 v[54:57], v[186:189], v[202:205], v[54:57]
	v_mfma_f32_16x16x32_bf16 v[50:53], v[194:197], v[202:205], v[50:53]
	v_mfma_f32_16x16x32_bf16 v[38:41], v[186:189], v[210:213], v[38:41]
	v_mfma_f32_16x16x32_bf16 v[34:37], v[194:197], v[210:213], v[34:37]
	v_mfma_f32_16x16x32_bf16 v[22:25], v[186:189], v[218:221], v[22:25]
	v_mfma_f32_16x16x32_bf16 v[18:21], v[194:197], v[218:221], v[18:21]
	v_mfma_f32_16x16x32_bf16 v[6:9], v[186:189], v[226:229], v[6:9]
	v_mfma_f32_16x16x32_bf16 v[2:5], v[194:197], v[226:229], v[2:5]
	s_barrier
	s_setprio 0
	s_add_i32 s63, s63, 2
	s_add_u32 s0, s0, 0x100
	s_addc_u32 s1, s1, 0
	s_add_u32 s61, s61, 0x100
	s_addc_u32 s62, s62, 0
	s_cmp_gt_u32 s63, 29

.LBB0_1555:
	ds_read_b128 v[144:147], v151
	ds_read_b128 v[154:157], v151 offset:1024
	ds_read_b128 v[158:161], v151 offset:2048
	ds_read_b128 v[162:165], v151 offset:3072
	ds_read_b128 v[166:169], v152
	ds_read_b128 v[170:173], v152 offset:1024
	ds_read_b128 v[174:177], v152 offset:2048
	ds_read_b128 v[178:181], v152 offset:3072
	ds_read_b128 v[182:185], v153
	ds_read_b128 v[186:189], v153 offset:1024
	ds_read_b128 v[190:193], v153 offset:2048
	ds_read_b128 v[194:197], v153 offset:3072
	ds_read_b128 v[198:201], v153 offset:4096
	ds_read_b128 v[202:205], v153 offset:5120
	ds_read_b128 v[206:209], v153 offset:6144
	ds_read_b128 v[210:213], v153 offset:7168
	s_add_i32 s36, s36, 1
	s_mul_i32 s2, s36, s39
	s_mul_hi_u32 s3, s36, s33
	s_add_i32 s3, s3, s2
	s_mul_i32 s2, s36, s33
	s_add_u32 s2, s2, s18
	s_addc_u32 s3, s3, s19
	v_cmp_gt_i64_e32 vcc, s[2:3], v[142:143]
	v_cmp_lt_i64_e64 s[4:5], s[2:3], v[140:141]
	s_cbranch_vccnz .LBB0_1561
	s_ashr_i32 s3, s2, 31
	s_lshr_b32 s3, s3, 29
	s_add_i32 s14, s2, s3
	s_and_b32 s3, s14, -8
	s_sub_i32 s15, s2, s3
	s_cmp_gt_i32 s15, -1
	s_mov_b64 s[2:3], -1
	s_cbranch_scc0 .LBB0_1558
	s_lshl_b32 s26, s15, 7
	s_mov_b64 s[2:3], 0

.LBB0_1565:
	s_add_u32 s16, s16, 0x160080
	s_addc_u32 s17, s17, 0
	s_add_u32 s46, s20, 0x100
	s_addc_u32 s47, s21, 0
	s_mov_b32 s48, -2
	s_add_u32 s20, s16, 0xffea0080
	s_addc_u32 s21, s17, -1
	s_cmpk_eq_i32 s48, 0x54
	s_cselect_b32 s27, s5, s21
	s_cselect_b32 s26, s4, s20
	s_cselect_b32 s21, s15, s47
	s_cselect_b32 s20, s14, s46
	s_add_i32 m0, s30, 0xc000
	s_nop 0
	global_load_lds_dwordx4 v136, s[16:17]
	s_add_i32 m0, s30, 0xe000
	s_nop 0
	global_load_lds_dwordx4 v138, s[16:17]
	s_waitcnt vmcnt(8)
	s_waitcnt lgkmcnt(0)
	s_setprio 1
	s_barrier
	v_mfma_f32_16x16x32_bf16 v[124:127], v[144:147], v[182:185], 0
	v_mfma_f32_16x16x32_bf16 v[120:123], v[158:161], v[182:185], 0
	v_mfma_f32_16x16x32_bf16 v[108:111], v[144:147], v[190:193], 0
	v_mfma_f32_16x16x32_bf16 v[104:107], v[158:161], v[190:193], 0
	v_mfma_f32_16x16x32_bf16 v[88:91], v[144:147], v[198:201], 0
	v_mfma_f32_16x16x32_bf16 v[92:95], v[158:161], v[198:201], 0
	v_mfma_f32_16x16x32_bf16 v[72:75], v[144:147], v[206:209], 0
	v_mfma_f32_16x16x32_bf16 v[76:79], v[158:161], v[206:209], 0
	v_mfma_f32_16x16x32_bf16 v[124:127], v[154:157], v[186:189], v[124:127]
	v_mfma_f32_16x16x32_bf16 v[120:123], v[162:165], v[186:189], v[120:123]
	v_mfma_f32_16x16x32_bf16 v[108:111], v[154:157], v[194:197], v[108:111]
	v_mfma_f32_16x16x32_bf16 v[104:107], v[162:165], v[194:197], v[104:107]
	v_mfma_f32_16x16x32_bf16 v[88:91], v[154:157], v[202:205], v[88:91]
	v_mfma_f32_16x16x32_bf16 v[92:95], v[162:165], v[202:205], v[92:95]
	v_mfma_f32_16x16x32_bf16 v[72:75], v[154:157], v[210:213], v[72:75]
	v_mfma_f32_16x16x32_bf16 v[76:79], v[162:165], v[210:213], v[76:79]
	s_setprio 0
	s_setprio 1
	v_mfma_f32_16x16x32_bf16 v[116:119], v[166:169], v[182:185], 0
	v_mfma_f32_16x16x32_bf16 v[112:115], v[174:177], v[182:185], 0
	v_mfma_f32_16x16x32_bf16 v[96:99], v[166:169], v[190:193], 0
	v_mfma_f32_16x16x32_bf16 v[100:103], v[174:177], v[190:193], 0
	v_mfma_f32_16x16x32_bf16 v[80:83], v[166:169], v[198:201], 0
	v_mfma_f32_16x16x32_bf16 v[84:87], v[174:177], v[198:201], 0
	v_mfma_f32_16x16x32_bf16 v[64:67], v[166:169], v[206:209], 0
	v_mfma_f32_16x16x32_bf16 v[68:71], v[174:177], v[206:209], 0
	v_mfma_f32_16x16x32_bf16 v[116:119], v[170:173], v[186:189], v[116:119]
	v_mfma_f32_16x16x32_bf16 v[112:115], v[178:181], v[186:189], v[112:115]
	v_mfma_f32_16x16x32_bf16 v[96:99], v[170:173], v[194:197], v[96:99]
	v_mfma_f32_16x16x32_bf16 v[100:103], v[178:181], v[194:197], v[100:103]
	v_mfma_f32_16x16x32_bf16 v[80:83], v[170:173], v[202:205], v[80:83]
	v_mfma_f32_16x16x32_bf16 v[84:87], v[178:181], v[202:205], v[84:87]
	v_mfma_f32_16x16x32_bf16 v[64:67], v[170:173], v[210:213], v[64:67]
	v_mfma_f32_16x16x32_bf16 v[68:71], v[178:181], v[210:213], v[68:71]
	s_barrier
	s_setprio 0
	s_add_i32 s49, s40, s29
	s_add_u32 s98, s20, 0x80
	s_addc_u32 s99, s21, 0
	s_mov_b32 m0, s49
	ds_read_b128 v[182:185], v153 offset:16384
	ds_read_b128 v[186:189], v153 offset:17408
	ds_read_b128 v[190:193], v153 offset:18432
	ds_read_b128 v[194:197], v153 offset:19456
	ds_read_b128 v[198:201], v153 offset:20480
	ds_read_b128 v[202:205], v153 offset:21504
	ds_read_b128 v[206:209], v153 offset:22528
	ds_read_b128 v[210:213], v153 offset:23552
	global_load_lds_dwordx4 v130, s[20:21]
	s_add_i32 m0, s49, 0x2000
	s_add_u32 s52, s20, 0x160000
	s_addc_u32 s53, s21, 0
	s_add_i32 s49, s41, s29
	global_load_lds_dwordx4 v134, s[20:21]
	s_mov_b32 m0, s49
	s_nop 0
	global_load_lds_dwordx4 v130, s[52:53]
	s_add_i32 m0, s49, 0x2000
	s_nop 0
	global_load_lds_dwordx4 v134, s[52:53]
	s_add_u32 s100, s26, 0x80
	s_addc_u32 s101, s27, 0
	s_mov_b32 m0, s30
	s_nop 0
	global_load_lds_dwordx4 v128, s[26:27]
	s_mov_b32 m0, s31
	s_nop 0
	global_load_lds_dwordx4 v132, s[26:27]
	s_waitcnt vmcnt(8)
	s_waitcnt lgkmcnt(0)
	s_setprio 1
	s_barrier
	v_mfma_f32_16x16x32_bf16 v[56:59], v[144:147], v[182:185], 0
	v_mfma_f32_16x16x32_bf16 v[60:63], v[158:161], v[182:185], 0
	v_mfma_f32_16x16x32_bf16 v[40:43], v[144:147], v[190:193], 0
	v_mfma_f32_16x16x32_bf16 v[44:47], v[158:161], v[190:193], 0
	v_mfma_f32_16x16x32_bf16 v[24:27], v[144:147], v[198:201], 0
	v_mfma_f32_16x16x32_bf16 v[28:31], v[158:161], v[198:201], 0
	v_mfma_f32_16x16x32_bf16 v[8:11], v[144:147], v[206:209], 0
	v_mfma_f32_16x16x32_bf16 v[12:15], v[158:161], v[206:209], 0
	v_mfma_f32_16x16x32_bf16 v[56:59], v[154:157], v[186:189], v[56:59]
	v_mfma_f32_16x16x32_bf16 v[60:63], v[162:165], v[186:189], v[60:63]
	v_mfma_f32_16x16x32_bf16 v[40:43], v[154:157], v[194:197], v[40:43]
	v_mfma_f32_16x16x32_bf16 v[44:47], v[162:165], v[194:197], v[44:47]
	v_mfma_f32_16x16x32_bf16 v[24:27], v[154:157], v[202:205], v[24:27]
	v_mfma_f32_16x16x32_bf16 v[28:31], v[162:165], v[202:205], v[28:31]
	v_mfma_f32_16x16x32_bf16 v[8:11], v[154:157], v[210:213], v[8:11]
	v_mfma_f32_16x16x32_bf16 v[12:15], v[162:165], v[210:213], v[12:15]
	s_setprio 0
	s_setprio 1
	v_mfma_f32_16x16x32_bf16 v[48:51], v[166:169], v[182:185], 0
	v_mfma_f32_16x16x32_bf16 v[52:55], v[174:177], v[182:185], 0
	v_mfma_f32_16x16x32_bf16 v[32:35], v[166:169], v[190:193], 0
	v_mfma_f32_16x16x32_bf16 v[36:39], v[174:177], v[190:193], 0
	v_mfma_f32_16x16x32_bf16 v[16:19], v[166:169], v[198:201], 0
	v_mfma_f32_16x16x32_bf16 v[20:23], v[174:177], v[198:201], 0
	v_mfma_f32_16x16x32_bf16 v[0:3], v[166:169], v[206:209], 0
	v_mfma_f32_16x16x32_bf16 v[4:7], v[174:177], v[206:209], 0
	v_mfma_f32_16x16x32_bf16 v[48:51], v[170:173], v[186:189], v[48:51]
	v_mfma_f32_16x16x32_bf16 v[52:55], v[178:181], v[186:189], v[52:55]
	v_mfma_f32_16x16x32_bf16 v[32:35], v[170:173], v[194:197], v[32:35]
	v_mfma_f32_16x16x32_bf16 v[36:39], v[178:181], v[194:197], v[36:39]
	v_mfma_f32_16x16x32_bf16 v[16:19], v[170:173], v[202:205], v[16:19]
	v_mfma_f32_16x16x32_bf16 v[20:23], v[178:181], v[202:205], v[20:23]
	v_mfma_f32_16x16x32_bf16 v[0:3], v[170:173], v[210:213], v[0:3]
	v_mfma_f32_16x16x32_bf16 v[4:7], v[178:181], v[210:213], v[4:7]
	s_barrier
	s_setprio 0
	s_add_i32 s49, 0, 0x18000
	s_add_i32 s52, 0, 0x1c000
	ds_read_b128 v[144:147], v151 offset:32768
	ds_read_b128 v[154:157], v151 offset:33792
	ds_read_b128 v[158:161], v151 offset:34816
	ds_read_b128 v[162:165], v151 offset:35840
	ds_read_b128 v[166:169], v152 offset:32768
	ds_read_b128 v[170:173], v152 offset:33792
	ds_read_b128 v[174:177], v152 offset:34816
	ds_read_b128 v[178:181], v152 offset:35840
	s_add_u32 s26, s26, 0x160000
	s_addc_u32 s27, s27, 0
	s_mov_b32 m0, s34
	ds_read_b128 v[182:185], v153 offset:32768
	ds_read_b128 v[186:189], v153 offset:33792
	ds_read_b128 v[190:193], v153 offset:34816
	ds_read_b128 v[194:197], v153 offset:35840
	ds_read_b128 v[198:201], v153 offset:36864
	ds_read_b128 v[202:205], v153 offset:37888
	ds_read_b128 v[206:209], v153 offset:38912
	ds_read_b128 v[210:213], v153 offset:39936
	global_load_lds_dwordx4 v128, s[26:27]
	s_mov_b32 m0, s35
	s_nop 0
	global_load_lds_dwordx4 v132, s[26:27]
	s_waitcnt vmcnt(8)
	s_waitcnt lgkmcnt(0)
	s_setprio 1
	s_barrier
	v_mfma_f32_16x16x32_bf16 v[124:127], v[144:147], v[182:185], v[124:127]
	v_mfma_f32_16x16x32_bf16 v[120:123], v[158:161], v[182:185], v[120:123]
	v_mfma_f32_16x16x32_bf16 v[108:111], v[144:147], v[190:193], v[108:111]
	v_mfma_f32_16x16x32_bf16 v[104:107], v[158:161], v[190:193], v[104:107]
	v_mfma_f32_16x16x32_bf16 v[88:91], v[144:147], v[198:201], v[88:91]
	v_mfma_f32_16x16x32_bf16 v[92:95], v[158:161], v[198:201], v[92:95]
	v_mfma_f32_16x16x32_bf16 v[72:75], v[144:147], v[206:209], v[72:75]
	v_mfma_f32_16x16x32_bf16 v[76:79], v[158:161], v[206:209], v[76:79]
	v_mfma_f32_16x16x32_bf16 v[124:127], v[154:157], v[186:189], v[124:127]
	v_mfma_f32_16x16x32_bf16 v[120:123], v[162:165], v[186:189], v[120:123]
	v_mfma_f32_16x16x32_bf16 v[108:111], v[154:157], v[194:197], v[108:111]
	v_mfma_f32_16x16x32_bf16 v[104:107], v[162:165], v[194:197], v[104:107]
	v_mfma_f32_16x16x32_bf16 v[88:91], v[154:157], v[202:205], v[88:91]
	v_mfma_f32_16x16x32_bf16 v[92:95], v[162:165], v[202:205], v[92:95]
	v_mfma_f32_16x16x32_bf16 v[72:75], v[154:157], v[210:213], v[72:75]
	v_mfma_f32_16x16x32_bf16 v[76:79], v[162:165], v[210:213], v[76:79]
	s_setprio 0
	s_setprio 1
	v_mfma_f32_16x16x32_bf16 v[116:119], v[166:169], v[182:185], v[116:119]
	v_mfma_f32_16x16x32_bf16 v[112:115], v[174:177], v[182:185], v[112:115]
	v_mfma_f32_16x16x32_bf16 v[96:99], v[166:169], v[190:193], v[96:99]
	v_mfma_f32_16x16x32_bf16 v[100:103], v[174:177], v[190:193], v[100:103]
	v_mfma_f32_16x16x32_bf16 v[80:83], v[166:169], v[198:201], v[80:83]
	v_mfma_f32_16x16x32_bf16 v[84:87], v[174:177], v[198:201], v[84:87]
	v_mfma_f32_16x16x32_bf16 v[64:67], v[166:169], v[206:209], v[64:67]
	v_mfma_f32_16x16x32_bf16 v[68:71], v[174:177], v[206:209], v[68:71]
	v_mfma_f32_16x16x32_bf16 v[116:119], v[170:173], v[186:189], v[116:119]
	v_mfma_f32_16x16x32_bf16 v[112:115], v[178:181], v[186:189], v[112:115]
	v_mfma_f32_16x16x32_bf16 v[96:99], v[170:173], v[194:197], v[96:99]
	v_mfma_f32_16x16x32_bf16 v[100:103], v[178:181], v[194:197], v[100:103]
	v_mfma_f32_16x16x32_bf16 v[80:83], v[170:173], v[202:205], v[80:83]
	v_mfma_f32_16x16x32_bf16 v[84:87], v[178:181], v[202:205], v[84:87]
	v_mfma_f32_16x16x32_bf16 v[64:67], v[170:173], v[210:213], v[64:67]
	v_mfma_f32_16x16x32_bf16 v[68:71], v[178:181], v[210:213], v[68:71]
	s_barrier
	s_setprio 0
	s_add_i32 s26, s49, s29
	s_mov_b32 m0, s26
	ds_read_b128 v[182:185], v153 offset:49152
	ds_read_b128 v[186:189], v153 offset:50176
	ds_read_b128 v[190:193], v153 offset:51200
	ds_read_b128 v[194:197], v153 offset:52224
	ds_read_b128 v[198:201], v153 offset:53248
	ds_read_b128 v[202:205], v153 offset:54272
	ds_read_b128 v[206:209], v153 offset:55296
	ds_read_b128 v[210:213], v153 offset:56320
	global_load_lds_dwordx4 v130, s[98:99]
	s_add_i32 m0, s26, 0x2000
	s_add_u32 s20, s20, 0x160080
	s_addc_u32 s21, s21, 0
	s_add_i32 s26, s52, s29
	global_load_lds_dwordx4 v134, s[98:99]
	s_mov_b32 m0, s26
	s_nop 0
	global_load_lds_dwordx4 v130, s[20:21]
	s_add_i32 m0, s26, 0x2000
	s_nop 0
	global_load_lds_dwordx4 v134, s[20:21]
	s_mov_b32 m0, s37
	s_nop 0
	global_load_lds_dwordx4 v128, s[100:101]
	s_mov_b32 m0, s38
	s_nop 0
	global_load_lds_dwordx4 v132, s[100:101]
	s_waitcnt vmcnt(8)
	s_waitcnt lgkmcnt(0)
	s_setprio 1
	s_barrier
	v_mfma_f32_16x16x32_bf16 v[56:59], v[144:147], v[182:185], v[56:59]
	v_mfma_f32_16x16x32_bf16 v[60:63], v[158:161], v[182:185], v[60:63]
	v_mfma_f32_16x16x32_bf16 v[40:43], v[144:147], v[190:193], v[40:43]
	v_mfma_f32_16x16x32_bf16 v[44:47], v[158:161], v[190:193], v[44:47]
	v_mfma_f32_16x16x32_bf16 v[24:27], v[144:147], v[198:201], v[24:27]
	v_mfma_f32_16x16x32_bf16 v[28:31], v[158:161], v[198:201], v[28:31]
	v_mfma_f32_16x16x32_bf16 v[8:11], v[144:147], v[206:209], v[8:11]
	v_mfma_f32_16x16x32_bf16 v[12:15], v[158:161], v[206:209], v[12:15]
	v_mfma_f32_16x16x32_bf16 v[56:59], v[154:157], v[186:189], v[56:59]
	v_mfma_f32_16x16x32_bf16 v[60:63], v[162:165], v[186:189], v[60:63]
	v_mfma_f32_16x16x32_bf16 v[40:43], v[154:157], v[194:197], v[40:43]
	v_mfma_f32_16x16x32_bf16 v[44:47], v[162:165], v[194:197], v[44:47]
	v_mfma_f32_16x16x32_bf16 v[24:27], v[154:157], v[202:205], v[24:27]
	v_mfma_f32_16x16x32_bf16 v[28:31], v[162:165], v[202:205], v[28:31]
	v_mfma_f32_16x16x32_bf16 v[8:11], v[154:157], v[210:213], v[8:11]
	v_mfma_f32_16x16x32_bf16 v[12:15], v[162:165], v[210:213], v[12:15]
	s_setprio 0
	s_setprio 1
	v_mfma_f32_16x16x32_bf16 v[48:51], v[166:169], v[182:185], v[48:51]
	v_mfma_f32_16x16x32_bf16 v[52:55], v[174:177], v[182:185], v[52:55]
	v_mfma_f32_16x16x32_bf16 v[32:35], v[166:169], v[190:193], v[32:35]
	v_mfma_f32_16x16x32_bf16 v[36:39], v[174:177], v[190:193], v[36:39]
	v_mfma_f32_16x16x32_bf16 v[16:19], v[166:169], v[198:201], v[16:19]
	v_mfma_f32_16x16x32_bf16 v[20:23], v[174:177], v[198:201], v[20:23]
	v_mfma_f32_16x16x32_bf16 v[0:3], v[166:169], v[206:209], v[0:3]
	v_mfma_f32_16x16x32_bf16 v[4:7], v[174:177], v[206:209], v[4:7]
	v_mfma_f32_16x16x32_bf16 v[48:51], v[170:173], v[186:189], v[48:51]
	v_mfma_f32_16x16x32_bf16 v[52:55], v[178:181], v[186:189], v[52:55]
	v_mfma_f32_16x16x32_bf16 v[32:35], v[170:173], v[194:197], v[32:35]
	v_mfma_f32_16x16x32_bf16 v[36:39], v[178:181], v[194:197], v[36:39]
	v_mfma_f32_16x16x32_bf16 v[16:19], v[170:173], v[202:205], v[16:19]
	v_mfma_f32_16x16x32_bf16 v[20:23], v[178:181], v[202:205], v[20:23]
	v_mfma_f32_16x16x32_bf16 v[0:3], v[170:173], v[210:213], v[0:3]
	v_mfma_f32_16x16x32_bf16 v[4:7], v[178:181], v[210:213], v[4:7]
	s_barrier
	s_setprio 0
	s_add_i32 s48, s48, 2
	s_add_u32 s16, s16, 0x100
	s_addc_u32 s17, s17, 0
	s_add_u32 s46, s46, 0x100
	s_addc_u32 s47, s47, 0
	s_cmpk_gt_u32 s48, 0x55
